# EpiRes (P3, P5): the 16 residual loads of a tile issued up front with counted vmcnt instead of load-wait per group
# baseline (speedup 1.0000x reference)
; __device__ __forceinline__ unsigned cvtpk(float lo, float hi) { f32x2 v = {lo, hi}; bf16x2_t b = __builtin_convertvector(v, bf16x2_t); return __builtin_bit_cast(unsigned, b); }
;     __device__ __forceinline__ void operator()(const f32x4 (&acc)[2][2][4][2], const Unit& u, int wr, int wc, int fr, int fq) const {
;     ...
;         for (int ai = 0; ai < 2; ++ai)
; #pragma unroll
;             for (int m = 0; m < 4; ++m) {
;                 const int row = u.pm * BM + ai * HALF + wr * 64 + m * 16 + fr;
;                 float ss = 0.f;
; #pragma unroll
;                 for (int bj = 0; bj < 2; ++bj) { const int col = u.pn * BM + bj * HALF + wc * 32 + 8 * fq;
;                     f32x4 v0, v1;
;                     if (xin_p) { const float* xr = (row < MP ? xin_p + (size_t)row * DM : xin_s + (size_t)(row - MP) * DM) + col; v0 = *(const f32x4*)xr; v1 = *(const f32x4*)(xr + 4); }
;                     else { const u32x4 w = *(const u32x4*)(XR + (size_t)row * DM + col);
;                         v0 = (f32x4){__uint_as_float(w.x << 16), __uint_as_float(w.x & 0xffff0000u), __uint_as_float(w.y << 16), __uint_as_float(w.y & 0xffff0000u)};
;                         v1 = (f32x4){__uint_as_float(w.z << 16), __uint_as_float(w.z & 0xffff0000u), __uint_as_float(w.w << 16), __uint_as_float(w.w & 0xffff0000u)}; }
;                     v0 = v0 + acc[ai][bj][m][0]; v1 = v1 + acc[ai][bj][m][1];
;                     if (fout) { *(f32x4*)(fout + (size_t)row * DM + col) = v0; *(f32x4*)(fout + (size_t)row * DM + col + 4) = v1; }
;                     else { u32x4 w; w.x = cvtpk(v0[0], v0[1]); w.y = cvtpk(v0[2], v0[3]); w.z = cvtpk(v1[0], v1[1]); w.w = cvtpk(v1[2], v1[3]); *(u32x4*)(XR + (size_t)row * DM + col) = w; }
;                     if (PS) ss += (v0[0] * v0[0] + v0[1] * v0[1]) + (v0[2] * v0[2] + v0[3] * v0[3]) + (v1[0] * v1[0] + v1[1] * v1[1]) + (v1[2] * v1[2] + v1[3] * v1[3]); }
;                 if (PS) { ss = bfly_add<16>(ss); ss = bfly_add<32>(ss); if (fq == 0) PS[(size_t)row * 16 + 4 * u.pn + wc] = ss; }
.LBB0_700:
	v_lshl_add_u32 v140, s43, 8, v152
	v_ashrrev_i32_e32 v141, 31, v140
	v_lshl_or_b32 v138, s33, 8, v154
	v_lshlrev_b64 v[142:143], 11, v[140:141]
	v_lshl_add_u64 v[142:143], s[10:11], 0, v[142:143]
	v_ashrrev_i32_e32 v139, 31, v138
	v_lshl_add_u64 v[142:143], v[138:139], 1, v[142:143]
	v_mov_b32_e32 v166, v142
	v_mov_b32_e32 v167, v143
	s_mov_b64 s[98:99], 0x8000
	s_mov_b64 s[100:101], 0x28000
	global_load_dwordx4 v[190:193], v[166:167], off
	global_load_dwordx4 v[194:197], v[166:167], off offset:256
	v_lshl_add_u64 v[166:167], v[166:167], 0, s[98:99]
	global_load_dwordx4 v[198:201], v[166:167], off
	global_load_dwordx4 v[202:205], v[166:167], off offset:256
	v_lshl_add_u64 v[166:167], v[166:167], 0, s[98:99]
	global_load_dwordx4 v[206:209], v[166:167], off
	global_load_dwordx4 v[210:213], v[166:167], off offset:256
	v_lshl_add_u64 v[166:167], v[166:167], 0, s[98:99]
	global_load_dwordx4 v[214:217], v[166:167], off
	global_load_dwordx4 v[218:221], v[166:167], off offset:256
	v_lshl_add_u64 v[166:167], v[166:167], 0, s[100:101]
	global_load_dwordx4 v[222:225], v[166:167], off
	global_load_dwordx4 v[226:229], v[166:167], off offset:256
	v_lshl_add_u64 v[166:167], v[166:167], 0, s[98:99]
	global_load_dwordx4 v[230:233], v[166:167], off
	global_load_dwordx4 v[234:237], v[166:167], off offset:256
	v_lshl_add_u64 v[166:167], v[166:167], 0, s[98:99]
	global_load_dwordx4 v[238:241], v[166:167], off
	global_load_dwordx4 v[242:245], v[166:167], off offset:256
	v_lshl_add_u64 v[166:167], v[166:167], 0, s[98:99]
	global_load_dwordx4 v[246:249], v[166:167], off
	global_load_dwordx4 v[250:253], v[166:167], off offset:256
	s_lshl_b32 s24, s33, 2
	s_ashr_i32 s25, s24, 31
	s_waitcnt vmcnt(15)
	v_mov_b32_e32 v156, v190
	v_mov_b32_e32 v157, v191
	v_mov_b32_e32 v158, v192
	v_mov_b32_e32 v159, v193
	v_lshlrev_b32_e32 v160, 16, v156
	v_and_b32_e32 v161, 0xffff0000, v156
	v_lshlrev_b32_e32 v156, 16, v157
	v_and_b32_e32 v157, 0xffff0000, v157
	v_lshlrev_b32_e32 v162, 16, v158
	v_and_b32_e32 v163, 0xffff0000, v158
	v_lshlrev_b32_e32 v158, 16, v159
	v_and_b32_e32 v159, 0xffff0000, v159
	v_pk_add_f32 v[126:127], v[126:127], v[156:157]
	v_pk_add_f32 v[124:125], v[124:125], v[160:161]
	v_pk_add_f32 v[156:157], v[122:123], v[158:159]
	v_pk_add_f32 v[158:159], v[120:121], v[162:163]
	v_cvt_pk_bf16_f32 v120, v124, v125
	v_cvt_pk_bf16_f32 v121, v126, v127
	v_cvt_pk_bf16_f32 v122, v158, v159
	v_cvt_pk_bf16_f32 v123, v156, v157
	global_store_dwordx4 v[142:143], v[120:123], off
	s_nop 1
	v_mul_f32_e32 v120, v125, v125
	v_mul_f32_e32 v121, v127, v127
	v_fmac_f32_e32 v120, v124, v124
	v_fmac_f32_e32 v121, v126, v126
	v_add_f32_e32 v120, v120, v121
	v_mul_f32_e32 v121, v159, v159
	v_fmac_f32_e32 v121, v158, v158
	v_add_f32_e32 v120, v121, v120
	v_mul_f32_e32 v121, v157, v157
	v_fmac_f32_e32 v121, v156, v156
	v_add_f32_e32 v156, v121, v120
	s_waitcnt vmcnt(15)
	v_mov_b32_e32 v120, v194
	v_mov_b32_e32 v121, v195
	v_mov_b32_e32 v122, v196
	v_mov_b32_e32 v123, v197
	v_lshlrev_b32_e32 v124, 16, v120
	v_and_b32_e32 v125, 0xffff0000, v120
	v_lshlrev_b32_e32 v120, 16, v121
	v_and_b32_e32 v121, 0xffff0000, v121
	v_lshlrev_b32_e32 v126, 16, v122
	v_and_b32_e32 v127, 0xffff0000, v122
	v_lshlrev_b32_e32 v122, 16, v123
	v_and_b32_e32 v123, 0xffff0000, v123
	v_pk_add_f32 v[118:119], v[118:119], v[120:121]
	v_pk_add_f32 v[116:117], v[116:117], v[124:125]
	v_pk_add_f32 v[120:121], v[114:115], v[122:123]
	v_pk_add_f32 v[122:123], v[112:113], v[126:127]
	v_cvt_pk_bf16_f32 v112, v116, v117
	v_cvt_pk_bf16_f32 v113, v118, v119
	v_cvt_pk_bf16_f32 v114, v122, v123
	v_cvt_pk_bf16_f32 v115, v120, v121
	global_store_dwordx4 v[142:143], v[112:115], off offset:256
	s_nop 1
	v_mul_f32_e32 v112, v117, v117
	v_mul_f32_e32 v113, v119, v119
	v_fmac_f32_e32 v112, v116, v116
	v_fmac_f32_e32 v113, v118, v118
	v_add_f32_e32 v112, v112, v113
	v_mul_f32_e32 v113, v123, v123
	v_fmac_f32_e32 v113, v122, v122
	v_add_f32_e32 v112, v113, v112
	v_mul_f32_e32 v113, v121, v121
	v_fmac_f32_e32 v113, v120, v120
	v_add_f32_e32 v112, v113, v112
	v_add_f32_e32 v112, v156, v112
	v_mov_b32_e32 v113, v112
	s_nop 1
	v_permlane16_swap_b32_e32 v112, v113
	s_waitcnt lgkmcnt(0)
	v_add_f32_e32 v112, v112, v113
	v_mov_b32_e32 v113, v112
	s_nop 1
	v_permlane32_swap_b32_e32 v112, v113
	s_and_saveexec_b64 s[26:27], s[4:5]
	s_cbranch_execz .LBB0_702
	v_lshlrev_b64 v[114:115], 6, v[140:141]
	v_lshl_add_u64 v[114:115], s[12:13], 0, v[114:115]
	v_lshl_add_u64 v[114:115], s[24:25], 2, v[114:115]
	s_lshl_b32 s84, s39, 2
	v_lshl_add_u64 v[114:115], v[114:115], 0, s[84:85]
	v_add_f32_e32 v112, v112, v113
	global_store_dword v[114:115], v112, off
; __device__ __forceinline__ unsigned cvtpk(float lo, float hi) { f32x2 v = {lo, hi}; bf16x2_t b = __builtin_convertvector(v, bf16x2_t); return __builtin_bit_cast(unsigned, b); }
;     __device__ __forceinline__ void operator()(const f32x4 (&acc)[2][2][4][2], const Unit& u, int wr, int wc, int fr, int fq) const {
;     ...
;         for (int ai = 0; ai < 2; ++ai)
; #pragma unroll
;             for (int m = 0; m < 4; ++m) {
;                 const int row = u.pm * BM + ai * HALF + wr * 64 + m * 16 + fr;
;                 float ss = 0.f;
; #pragma unroll
;                 for (int bj = 0; bj < 2; ++bj) { const int col = u.pn * BM + bj * HALF + wc * 32 + 8 * fq;
;                     f32x4 v0, v1;
;                     if (xin_p) { const float* xr = (row < MP ? xin_p + (size_t)row * DM : xin_s + (size_t)(row - MP) * DM) + col; v0 = *(const f32x4*)xr; v1 = *(const f32x4*)(xr + 4); }
;                     else { const u32x4 w = *(const u32x4*)(XR + (size_t)row * DM + col);
;                         v0 = (f32x4){__uint_as_float(w.x << 16), __uint_as_float(w.x & 0xffff0000u), __uint_as_float(w.y << 16), __uint_as_float(w.y & 0xffff0000u)};
;                         v1 = (f32x4){__uint_as_float(w.z << 16), __uint_as_float(w.z & 0xffff0000u), __uint_as_float(w.w << 16), __uint_as_float(w.w & 0xffff0000u)}; }
;                     v0 = v0 + acc[ai][bj][m][0]; v1 = v1 + acc[ai][bj][m][1];
;                     if (fout) { *(f32x4*)(fout + (size_t)row * DM + col) = v0; *(f32x4*)(fout + (size_t)row * DM + col + 4) = v1; }
;                     else { u32x4 w; w.x = cvtpk(v0[0], v0[1]); w.y = cvtpk(v0[2], v0[3]); w.z = cvtpk(v1[0], v1[1]); w.w = cvtpk(v1[2], v1[3]); *(u32x4*)(XR + (size_t)row * DM + col) = w; }
;                     if (PS) ss += (v0[0] * v0[0] + v0[1] * v0[1]) + (v0[2] * v0[2] + v0[3] * v0[3]) + (v1[0] * v1[0] + v1[1] * v1[1]) + (v1[2] * v1[2] + v1[3] * v1[3]); }
;                 if (PS) { ss = bfly_add<16>(ss); ss = bfly_add<32>(ss); if (fq == 0) PS[(size_t)row * 16 + 4 * u.pn + wc] = ss; }
.LBB0_702:
	s_or_b64 exec, exec, s[26:27]
	v_or_b32_e32 v112, 16, v140
	v_ashrrev_i32_e32 v113, 31, v112
	v_lshlrev_b64 v[114:115], 11, v[112:113]
	v_lshl_add_u64 v[114:115], s[10:11], 0, v[114:115]
	v_lshl_add_u64 v[114:115], v[138:139], 1, v[114:115]
	s_waitcnt vmcnt(15)
	v_mov_b32_e32 v116, v198
	v_mov_b32_e32 v117, v199
	v_mov_b32_e32 v118, v200
	v_mov_b32_e32 v119, v201
	v_lshlrev_b32_e32 v120, 16, v116
	v_and_b32_e32 v121, 0xffff0000, v116
	v_lshlrev_b32_e32 v116, 16, v117
	v_and_b32_e32 v117, 0xffff0000, v117
	v_lshlrev_b32_e32 v122, 16, v118
	v_and_b32_e32 v123, 0xffff0000, v118
	v_lshlrev_b32_e32 v118, 16, v119
	v_and_b32_e32 v119, 0xffff0000, v119
	v_pk_add_f32 v[110:111], v[110:111], v[116:117]
	v_pk_add_f32 v[108:109], v[108:109], v[120:121]
	v_pk_add_f32 v[116:117], v[106:107], v[118:119]
	v_pk_add_f32 v[118:119], v[104:105], v[122:123]
	v_cvt_pk_bf16_f32 v104, v108, v109
	v_cvt_pk_bf16_f32 v105, v110, v111
	v_cvt_pk_bf16_f32 v106, v118, v119
	v_cvt_pk_bf16_f32 v107, v116, v117
	global_store_dwordx4 v[114:115], v[104:107], off
	s_nop 1
	v_mul_f32_e32 v104, v109, v109
	v_mul_f32_e32 v105, v111, v111
	v_fmac_f32_e32 v104, v108, v108
	v_fmac_f32_e32 v105, v110, v110
	v_add_f32_e32 v104, v104, v105
	v_mul_f32_e32 v105, v119, v119
	v_fmac_f32_e32 v105, v118, v118
	v_add_f32_e32 v104, v105, v104
	v_mul_f32_e32 v105, v117, v117
	v_fmac_f32_e32 v105, v116, v116
	v_add_f32_e32 v116, v105, v104
	s_waitcnt vmcnt(15)
	v_mov_b32_e32 v104, v202
	v_mov_b32_e32 v105, v203
	v_mov_b32_e32 v106, v204
	v_mov_b32_e32 v107, v205
	v_lshlrev_b32_e32 v108, 16, v104
	v_and_b32_e32 v109, 0xffff0000, v104
	v_lshlrev_b32_e32 v104, 16, v105
	v_and_b32_e32 v105, 0xffff0000, v105
	v_lshlrev_b32_e32 v110, 16, v106
	v_and_b32_e32 v111, 0xffff0000, v106
	v_lshlrev_b32_e32 v106, 16, v107
	v_and_b32_e32 v107, 0xffff0000, v107
	v_pk_add_f32 v[102:103], v[102:103], v[104:105]
	v_pk_add_f32 v[100:101], v[100:101], v[108:109]
	v_pk_add_f32 v[104:105], v[98:99], v[106:107]
	v_pk_add_f32 v[106:107], v[96:97], v[110:111]
	v_cvt_pk_bf16_f32 v96, v100, v101
	v_cvt_pk_bf16_f32 v97, v102, v103
	v_cvt_pk_bf16_f32 v98, v106, v107
	v_cvt_pk_bf16_f32 v99, v104, v105
	global_store_dwordx4 v[114:115], v[96:99], off offset:256
	s_nop 1
	v_mul_f32_e32 v96, v101, v101
	v_mul_f32_e32 v97, v103, v103
	v_fmac_f32_e32 v96, v100, v100
	v_fmac_f32_e32 v97, v102, v102
	v_add_f32_e32 v96, v96, v97
	v_mul_f32_e32 v97, v107, v107
	v_fmac_f32_e32 v97, v106, v106
	v_add_f32_e32 v96, v97, v96
	v_mul_f32_e32 v97, v105, v105
	v_fmac_f32_e32 v97, v104, v104
	v_add_f32_e32 v96, v97, v96
	v_add_f32_e32 v96, v116, v96
	v_mov_b32_e32 v97, v96
	s_nop 1
	v_permlane16_swap_b32_e32 v96, v97
	s_waitcnt lgkmcnt(0)
	v_add_f32_e32 v96, v96, v97
	v_mov_b32_e32 v97, v96
	s_nop 1
	v_permlane32_swap_b32_e32 v96, v97
	s_and_saveexec_b64 s[26:27], s[4:5]
	s_cbranch_execz .LBB0_704
	v_lshlrev_b64 v[98:99], 6, v[112:113]
	v_lshl_add_u64 v[98:99], s[12:13], 0, v[98:99]
	v_lshl_add_u64 v[98:99], s[24:25], 2, v[98:99]
	s_lshl_b32 s84, s39, 2
	v_lshl_add_u64 v[98:99], v[98:99], 0, s[84:85]
	v_add_f32_e32 v96, v96, v97
	global_store_dword v[98:99], v96, off
.LBB0_704:
	s_or_b64 exec, exec, s[26:27]
	v_or_b32_e32 v96, 32, v140
	v_ashrrev_i32_e32 v97, 31, v96
	v_lshlrev_b64 v[98:99], 11, v[96:97]
	v_lshl_add_u64 v[98:99], s[10:11], 0, v[98:99]
	v_lshl_add_u64 v[98:99], v[138:139], 1, v[98:99]
	s_waitcnt vmcnt(15)
	v_mov_b32_e32 v100, v206
	v_mov_b32_e32 v101, v207
	v_mov_b32_e32 v102, v208
	v_mov_b32_e32 v103, v209
	v_lshlrev_b32_e32 v104, 16, v100
	v_and_b32_e32 v105, 0xffff0000, v100
	v_lshlrev_b32_e32 v100, 16, v101
	v_and_b32_e32 v101, 0xffff0000, v101
	v_lshlrev_b32_e32 v106, 16, v102
	v_and_b32_e32 v107, 0xffff0000, v102
	v_lshlrev_b32_e32 v102, 16, v103
	v_and_b32_e32 v103, 0xffff0000, v103
	v_pk_add_f32 v[94:95], v[94:95], v[100:101]
	v_pk_add_f32 v[92:93], v[92:93], v[104:105]
	v_pk_add_f32 v[100:101], v[90:91], v[102:103]
	v_pk_add_f32 v[102:103], v[88:89], v[106:107]
	v_cvt_pk_bf16_f32 v88, v92, v93
	v_cvt_pk_bf16_f32 v89, v94, v95
	v_cvt_pk_bf16_f32 v90, v102, v103
	v_cvt_pk_bf16_f32 v91, v100, v101
	global_store_dwordx4 v[98:99], v[88:91], off
	s_nop 1
	v_mul_f32_e32 v88, v93, v93
	v_mul_f32_e32 v89, v95, v95
	v_fmac_f32_e32 v88, v92, v92
	v_fmac_f32_e32 v89, v94, v94
	v_add_f32_e32 v88, v88, v89
	v_mul_f32_e32 v89, v103, v103
	v_fmac_f32_e32 v89, v102, v102
	v_add_f32_e32 v88, v89, v88
	v_mul_f32_e32 v89, v101, v101
	v_fmac_f32_e32 v89, v100, v100
	v_add_f32_e32 v100, v89, v88
	s_waitcnt vmcnt(15)
	v_mov_b32_e32 v88, v210
	v_mov_b32_e32 v89, v211
	v_mov_b32_e32 v90, v212
	v_mov_b32_e32 v91, v213
	v_lshlrev_b32_e32 v92, 16, v88
	v_and_b32_e32 v93, 0xffff0000, v88
	v_lshlrev_b32_e32 v88, 16, v89
	v_and_b32_e32 v89, 0xffff0000, v89
	v_lshlrev_b32_e32 v94, 16, v90
	v_and_b32_e32 v95, 0xffff0000, v90
	v_lshlrev_b32_e32 v90, 16, v91
	v_and_b32_e32 v91, 0xffff0000, v91
	v_pk_add_f32 v[86:87], v[86:87], v[88:89]
	v_pk_add_f32 v[84:85], v[84:85], v[92:93]
	v_pk_add_f32 v[88:89], v[82:83], v[90:91]
	v_pk_add_f32 v[90:91], v[80:81], v[94:95]
	v_cvt_pk_bf16_f32 v80, v84, v85
	v_cvt_pk_bf16_f32 v81, v86, v87
	v_cvt_pk_bf16_f32 v82, v90, v91
	v_cvt_pk_bf16_f32 v83, v88, v89
	global_store_dwordx4 v[98:99], v[80:83], off offset:256
	s_nop 1
	v_mul_f32_e32 v80, v85, v85
	v_mul_f32_e32 v81, v87, v87
	v_fmac_f32_e32 v80, v84, v84
	v_fmac_f32_e32 v81, v86, v86
	v_add_f32_e32 v80, v80, v81
	v_mul_f32_e32 v81, v91, v91
	v_fmac_f32_e32 v81, v90, v90
	v_add_f32_e32 v80, v81, v80
	v_mul_f32_e32 v81, v89, v89
	v_fmac_f32_e32 v81, v88, v88
	v_add_f32_e32 v80, v81, v80
	v_add_f32_e32 v80, v100, v80
	v_mov_b32_e32 v81, v80
	s_nop 1
	v_permlane16_swap_b32_e32 v80, v81
	s_waitcnt lgkmcnt(0)
	v_add_f32_e32 v80, v80, v81
	v_mov_b32_e32 v81, v80
	s_nop 1
	v_permlane32_swap_b32_e32 v80, v81
	s_and_saveexec_b64 s[26:27], s[4:5]
	s_cbranch_execz .LBB0_706
	v_lshlrev_b64 v[82:83], 6, v[96:97]
	v_lshl_add_u64 v[82:83], s[12:13], 0, v[82:83]
	v_lshl_add_u64 v[82:83], s[24:25], 2, v[82:83]
	s_lshl_b32 s84, s39, 2
	v_lshl_add_u64 v[82:83], v[82:83], 0, s[84:85]
	v_add_f32_e32 v80, v80, v81
	global_store_dword v[82:83], v80, off
; __device__ __forceinline__ unsigned cvtpk(float lo, float hi) { f32x2 v = {lo, hi}; bf16x2_t b = __builtin_convertvector(v, bf16x2_t); return __builtin_bit_cast(unsigned, b); }
;     __device__ __forceinline__ void operator()(const f32x4 (&acc)[2][2][4][2], const Unit& u, int wr, int wc, int fr, int fq) const {
;     ...
;         for (int ai = 0; ai < 2; ++ai)
; #pragma unroll
;             for (int m = 0; m < 4; ++m) {
;                 const int row = u.pm * BM + ai * HALF + wr * 64 + m * 16 + fr;
;                 float ss = 0.f;
; #pragma unroll
;                 for (int bj = 0; bj < 2; ++bj) { const int col = u.pn * BM + bj * HALF + wc * 32 + 8 * fq;
;                     f32x4 v0, v1;
;                     if (xin_p) { const float* xr = (row < MP ? xin_p + (size_t)row * DM : xin_s + (size_t)(row - MP) * DM) + col; v0 = *(const f32x4*)xr; v1 = *(const f32x4*)(xr + 4); }
;                     else { const u32x4 w = *(const u32x4*)(XR + (size_t)row * DM + col);
;                         v0 = (f32x4){__uint_as_float(w.x << 16), __uint_as_float(w.x & 0xffff0000u), __uint_as_float(w.y << 16), __uint_as_float(w.y & 0xffff0000u)};
;                         v1 = (f32x4){__uint_as_float(w.z << 16), __uint_as_float(w.z & 0xffff0000u), __uint_as_float(w.w << 16), __uint_as_float(w.w & 0xffff0000u)}; }
;                     v0 = v0 + acc[ai][bj][m][0]; v1 = v1 + acc[ai][bj][m][1];
;                     if (fout) { *(f32x4*)(fout + (size_t)row * DM + col) = v0; *(f32x4*)(fout + (size_t)row * DM + col + 4) = v1; }
;                     else { u32x4 w; w.x = cvtpk(v0[0], v0[1]); w.y = cvtpk(v0[2], v0[3]); w.z = cvtpk(v1[0], v1[1]); w.w = cvtpk(v1[2], v1[3]); *(u32x4*)(XR + (size_t)row * DM + col) = w; }
;                     if (PS) ss += (v0[0] * v0[0] + v0[1] * v0[1]) + (v0[2] * v0[2] + v0[3] * v0[3]) + (v1[0] * v1[0] + v1[1] * v1[1]) + (v1[2] * v1[2] + v1[3] * v1[3]); }
;                 if (PS) { ss = bfly_add<16>(ss); ss = bfly_add<32>(ss); if (fq == 0) PS[(size_t)row * 16 + 4 * u.pn + wc] = ss; }
.LBB0_706:
	s_or_b64 exec, exec, s[26:27]
	v_or_b32_e32 v80, 48, v140
	v_ashrrev_i32_e32 v81, 31, v80
	v_lshlrev_b64 v[82:83], 11, v[80:81]
	v_lshl_add_u64 v[82:83], s[10:11], 0, v[82:83]
	v_lshl_add_u64 v[82:83], v[138:139], 1, v[82:83]
	s_waitcnt vmcnt(15)
	v_mov_b32_e32 v84, v214
	v_mov_b32_e32 v85, v215
	v_mov_b32_e32 v86, v216
	v_mov_b32_e32 v87, v217
	v_lshlrev_b32_e32 v88, 16, v84
	v_and_b32_e32 v89, 0xffff0000, v84
	v_lshlrev_b32_e32 v84, 16, v85
	v_and_b32_e32 v85, 0xffff0000, v85
	v_lshlrev_b32_e32 v90, 16, v86
	v_and_b32_e32 v91, 0xffff0000, v86
	v_lshlrev_b32_e32 v86, 16, v87
	v_and_b32_e32 v87, 0xffff0000, v87
	v_pk_add_f32 v[78:79], v[78:79], v[84:85]
	v_pk_add_f32 v[76:77], v[76:77], v[88:89]
	v_pk_add_f32 v[84:85], v[74:75], v[86:87]
	v_pk_add_f32 v[86:87], v[72:73], v[90:91]
	v_cvt_pk_bf16_f32 v72, v76, v77
	v_cvt_pk_bf16_f32 v73, v78, v79
	v_cvt_pk_bf16_f32 v74, v86, v87
	v_cvt_pk_bf16_f32 v75, v84, v85
	global_store_dwordx4 v[82:83], v[72:75], off
	s_nop 1
	v_mul_f32_e32 v72, v77, v77
	v_mul_f32_e32 v73, v79, v79
	v_fmac_f32_e32 v72, v76, v76
	v_fmac_f32_e32 v73, v78, v78
	v_add_f32_e32 v72, v72, v73
	v_mul_f32_e32 v73, v87, v87
	v_fmac_f32_e32 v73, v86, v86
	v_add_f32_e32 v72, v73, v72
	v_mul_f32_e32 v73, v85, v85
	v_fmac_f32_e32 v73, v84, v84
	v_add_f32_e32 v84, v73, v72
	s_waitcnt vmcnt(15)
	v_mov_b32_e32 v72, v218
	v_mov_b32_e32 v73, v219
	v_mov_b32_e32 v74, v220
	v_mov_b32_e32 v75, v221
	v_lshlrev_b32_e32 v76, 16, v72
	v_and_b32_e32 v77, 0xffff0000, v72
	v_lshlrev_b32_e32 v72, 16, v73
	v_and_b32_e32 v73, 0xffff0000, v73
	v_lshlrev_b32_e32 v78, 16, v74
	v_and_b32_e32 v79, 0xffff0000, v74
	v_lshlrev_b32_e32 v74, 16, v75
	v_and_b32_e32 v75, 0xffff0000, v75
	v_pk_add_f32 v[70:71], v[70:71], v[72:73]
	v_pk_add_f32 v[68:69], v[68:69], v[76:77]
	v_pk_add_f32 v[72:73], v[66:67], v[74:75]
	v_pk_add_f32 v[74:75], v[64:65], v[78:79]
	v_cvt_pk_bf16_f32 v64, v68, v69
	v_cvt_pk_bf16_f32 v65, v70, v71
	v_cvt_pk_bf16_f32 v66, v74, v75
	v_cvt_pk_bf16_f32 v67, v72, v73
	global_store_dwordx4 v[82:83], v[64:67], off offset:256
	s_nop 1
	v_mul_f32_e32 v64, v69, v69
	v_mul_f32_e32 v65, v71, v71
	v_fmac_f32_e32 v64, v68, v68
	v_fmac_f32_e32 v65, v70, v70
	v_add_f32_e32 v64, v64, v65
	v_mul_f32_e32 v65, v75, v75
	v_fmac_f32_e32 v65, v74, v74
	v_add_f32_e32 v64, v65, v64
	v_mul_f32_e32 v65, v73, v73
	v_fmac_f32_e32 v65, v72, v72
	v_add_f32_e32 v64, v65, v64
	v_add_f32_e32 v64, v84, v64
	v_mov_b32_e32 v65, v64
	s_nop 1
	v_permlane16_swap_b32_e32 v64, v65
	s_waitcnt lgkmcnt(0)
	v_add_f32_e32 v64, v64, v65
	v_mov_b32_e32 v65, v64
	s_nop 1
	v_permlane32_swap_b32_e32 v64, v65
	s_and_saveexec_b64 s[26:27], s[4:5]
	s_cbranch_execz .LBB0_708
	v_lshlrev_b64 v[66:67], 6, v[80:81]
	v_lshl_add_u64 v[66:67], s[12:13], 0, v[66:67]
	v_lshl_add_u64 v[66:67], s[24:25], 2, v[66:67]
	s_lshl_b32 s84, s39, 2
	v_lshl_add_u64 v[66:67], v[66:67], 0, s[84:85]
	v_add_f32_e32 v64, v64, v65
	global_store_dword v[66:67], v64, off
.LBB0_708:
	s_or_b64 exec, exec, s[26:27]
	v_add_u32_e32 v64, 0x80, v140
	v_ashrrev_i32_e32 v65, 31, v64
	v_lshlrev_b64 v[66:67], 11, v[64:65]
	v_lshl_add_u64 v[66:67], s[10:11], 0, v[66:67]
	v_lshl_add_u64 v[66:67], v[138:139], 1, v[66:67]
	s_waitcnt vmcnt(15)
	v_mov_b32_e32 v68, v222
	v_mov_b32_e32 v69, v223
	v_mov_b32_e32 v70, v224
	v_mov_b32_e32 v71, v225
	v_lshlrev_b32_e32 v72, 16, v68
	v_and_b32_e32 v73, 0xffff0000, v68
	v_lshlrev_b32_e32 v68, 16, v69
	v_and_b32_e32 v69, 0xffff0000, v69
	v_lshlrev_b32_e32 v74, 16, v70
	v_and_b32_e32 v75, 0xffff0000, v70
	v_lshlrev_b32_e32 v70, 16, v71
	v_and_b32_e32 v71, 0xffff0000, v71
	v_pk_add_f32 v[62:63], v[62:63], v[68:69]
	v_pk_add_f32 v[60:61], v[60:61], v[72:73]
	v_pk_add_f32 v[68:69], v[58:59], v[70:71]
	v_pk_add_f32 v[70:71], v[56:57], v[74:75]
	v_cvt_pk_bf16_f32 v56, v60, v61
	v_cvt_pk_bf16_f32 v57, v62, v63
	v_cvt_pk_bf16_f32 v58, v70, v71
	v_cvt_pk_bf16_f32 v59, v68, v69
	global_store_dwordx4 v[66:67], v[56:59], off
	s_nop 1
	v_mul_f32_e32 v56, v61, v61
	v_mul_f32_e32 v57, v63, v63
	v_fmac_f32_e32 v56, v60, v60
	v_fmac_f32_e32 v57, v62, v62
	v_add_f32_e32 v56, v56, v57
	v_mul_f32_e32 v57, v71, v71
	v_fmac_f32_e32 v57, v70, v70
	v_add_f32_e32 v56, v57, v56
	v_mul_f32_e32 v57, v69, v69
	v_fmac_f32_e32 v57, v68, v68
	v_add_f32_e32 v68, v57, v56
	s_waitcnt vmcnt(15)
	v_mov_b32_e32 v56, v226
	v_mov_b32_e32 v57, v227
	v_mov_b32_e32 v58, v228
	v_mov_b32_e32 v59, v229
	v_lshlrev_b32_e32 v60, 16, v56
	v_and_b32_e32 v61, 0xffff0000, v56
	v_lshlrev_b32_e32 v56, 16, v57
	v_and_b32_e32 v57, 0xffff0000, v57
	v_lshlrev_b32_e32 v62, 16, v58
	v_and_b32_e32 v63, 0xffff0000, v58
	v_lshlrev_b32_e32 v58, 16, v59
	v_and_b32_e32 v59, 0xffff0000, v59
	v_pk_add_f32 v[54:55], v[54:55], v[56:57]
	v_pk_add_f32 v[52:53], v[52:53], v[60:61]
	v_pk_add_f32 v[56:57], v[50:51], v[58:59]
	v_pk_add_f32 v[58:59], v[48:49], v[62:63]
	v_cvt_pk_bf16_f32 v48, v52, v53
	v_cvt_pk_bf16_f32 v49, v54, v55
	v_cvt_pk_bf16_f32 v50, v58, v59
	v_cvt_pk_bf16_f32 v51, v56, v57
	global_store_dwordx4 v[66:67], v[48:51], off offset:256
	s_nop 1
	v_mul_f32_e32 v48, v53, v53
	v_mul_f32_e32 v49, v55, v55
	v_fmac_f32_e32 v48, v52, v52
	v_fmac_f32_e32 v49, v54, v54
	v_add_f32_e32 v48, v48, v49
	v_mul_f32_e32 v49, v59, v59
	v_fmac_f32_e32 v49, v58, v58
	v_add_f32_e32 v48, v49, v48
	v_mul_f32_e32 v49, v57, v57
	v_fmac_f32_e32 v49, v56, v56
	v_add_f32_e32 v48, v49, v48
	v_add_f32_e32 v48, v68, v48
	v_mov_b32_e32 v49, v48
	s_nop 1
	v_permlane16_swap_b32_e32 v48, v49
	s_waitcnt lgkmcnt(0)
	v_add_f32_e32 v48, v48, v49
	v_mov_b32_e32 v49, v48
	s_nop 1
	v_permlane32_swap_b32_e32 v48, v49
	s_and_saveexec_b64 s[26:27], s[4:5]
	s_cbranch_execz .LBB0_710
	v_lshlrev_b64 v[50:51], 6, v[64:65]
	v_lshl_add_u64 v[50:51], s[12:13], 0, v[50:51]
	v_lshl_add_u64 v[50:51], s[24:25], 2, v[50:51]
	s_lshl_b32 s84, s39, 2
	v_lshl_add_u64 v[50:51], v[50:51], 0, s[84:85]
	v_add_f32_e32 v48, v48, v49
	global_store_dword v[50:51], v48, off
; __device__ __forceinline__ unsigned cvtpk(float lo, float hi) { f32x2 v = {lo, hi}; bf16x2_t b = __builtin_convertvector(v, bf16x2_t); return __builtin_bit_cast(unsigned, b); }
;     __device__ __forceinline__ void operator()(const f32x4 (&acc)[2][2][4][2], const Unit& u, int wr, int wc, int fr, int fq) const {
;     ...
;         for (int ai = 0; ai < 2; ++ai)
; #pragma unroll
;             for (int m = 0; m < 4; ++m) {
;                 const int row = u.pm * BM + ai * HALF + wr * 64 + m * 16 + fr;
;                 float ss = 0.f;
; #pragma unroll
;                 for (int bj = 0; bj < 2; ++bj) { const int col = u.pn * BM + bj * HALF + wc * 32 + 8 * fq;
;                     f32x4 v0, v1;
;                     if (xin_p) { const float* xr = (row < MP ? xin_p + (size_t)row * DM : xin_s + (size_t)(row - MP) * DM) + col; v0 = *(const f32x4*)xr; v1 = *(const f32x4*)(xr + 4); }
;                     else { const u32x4 w = *(const u32x4*)(XR + (size_t)row * DM + col);
;                         v0 = (f32x4){__uint_as_float(w.x << 16), __uint_as_float(w.x & 0xffff0000u), __uint_as_float(w.y << 16), __uint_as_float(w.y & 0xffff0000u)};
;                         v1 = (f32x4){__uint_as_float(w.z << 16), __uint_as_float(w.z & 0xffff0000u), __uint_as_float(w.w << 16), __uint_as_float(w.w & 0xffff0000u)}; }
;                     v0 = v0 + acc[ai][bj][m][0]; v1 = v1 + acc[ai][bj][m][1];
;                     if (fout) { *(f32x4*)(fout + (size_t)row * DM + col) = v0; *(f32x4*)(fout + (size_t)row * DM + col + 4) = v1; }
;                     else { u32x4 w; w.x = cvtpk(v0[0], v0[1]); w.y = cvtpk(v0[2], v0[3]); w.z = cvtpk(v1[0], v1[1]); w.w = cvtpk(v1[2], v1[3]); *(u32x4*)(XR + (size_t)row * DM + col) = w; }
;                     if (PS) ss += (v0[0] * v0[0] + v0[1] * v0[1]) + (v0[2] * v0[2] + v0[3] * v0[3]) + (v1[0] * v1[0] + v1[1] * v1[1]) + (v1[2] * v1[2] + v1[3] * v1[3]); }
;                 if (PS) { ss = bfly_add<16>(ss); ss = bfly_add<32>(ss); if (fq == 0) PS[(size_t)row * 16 + 4 * u.pn + wc] = ss; }
.LBB0_710:
	s_or_b64 exec, exec, s[26:27]
	v_add_u32_e32 v48, 0x90, v140
	v_ashrrev_i32_e32 v49, 31, v48
	v_lshlrev_b64 v[50:51], 11, v[48:49]
	v_lshl_add_u64 v[50:51], s[10:11], 0, v[50:51]
	v_lshl_add_u64 v[50:51], v[138:139], 1, v[50:51]
	s_waitcnt vmcnt(15)
	v_mov_b32_e32 v52, v230
	v_mov_b32_e32 v53, v231
	v_mov_b32_e32 v54, v232
	v_mov_b32_e32 v55, v233
	v_lshlrev_b32_e32 v56, 16, v52
	v_and_b32_e32 v57, 0xffff0000, v52
	v_lshlrev_b32_e32 v52, 16, v53
	v_and_b32_e32 v53, 0xffff0000, v53
	v_lshlrev_b32_e32 v58, 16, v54
	v_and_b32_e32 v59, 0xffff0000, v54
	v_lshlrev_b32_e32 v54, 16, v55
	v_and_b32_e32 v55, 0xffff0000, v55
	v_pk_add_f32 v[46:47], v[46:47], v[52:53]
	v_pk_add_f32 v[44:45], v[44:45], v[56:57]
	v_pk_add_f32 v[52:53], v[42:43], v[54:55]
	v_pk_add_f32 v[54:55], v[40:41], v[58:59]
	v_cvt_pk_bf16_f32 v40, v44, v45
	v_cvt_pk_bf16_f32 v41, v46, v47
	v_cvt_pk_bf16_f32 v42, v54, v55
	v_cvt_pk_bf16_f32 v43, v52, v53
	global_store_dwordx4 v[50:51], v[40:43], off
	s_nop 1
	v_mul_f32_e32 v40, v45, v45
	v_mul_f32_e32 v41, v47, v47
	v_fmac_f32_e32 v40, v44, v44
	v_fmac_f32_e32 v41, v46, v46
	v_add_f32_e32 v40, v40, v41
	v_mul_f32_e32 v41, v55, v55
	v_fmac_f32_e32 v41, v54, v54
	v_add_f32_e32 v40, v41, v40
	v_mul_f32_e32 v41, v53, v53
	v_fmac_f32_e32 v41, v52, v52
	v_add_f32_e32 v52, v41, v40
	s_waitcnt vmcnt(15)
	v_mov_b32_e32 v40, v234
	v_mov_b32_e32 v41, v235
	v_mov_b32_e32 v42, v236
	v_mov_b32_e32 v43, v237
	v_lshlrev_b32_e32 v44, 16, v40
	v_and_b32_e32 v45, 0xffff0000, v40
	v_lshlrev_b32_e32 v40, 16, v41
	v_and_b32_e32 v41, 0xffff0000, v41
	v_lshlrev_b32_e32 v46, 16, v42
	v_and_b32_e32 v47, 0xffff0000, v42
	v_lshlrev_b32_e32 v42, 16, v43
	v_and_b32_e32 v43, 0xffff0000, v43
	v_pk_add_f32 v[38:39], v[38:39], v[40:41]
	v_pk_add_f32 v[36:37], v[36:37], v[44:45]
	v_pk_add_f32 v[40:41], v[34:35], v[42:43]
	v_pk_add_f32 v[42:43], v[32:33], v[46:47]
	v_cvt_pk_bf16_f32 v32, v36, v37
	v_cvt_pk_bf16_f32 v33, v38, v39
	v_cvt_pk_bf16_f32 v34, v42, v43
	v_cvt_pk_bf16_f32 v35, v40, v41
	global_store_dwordx4 v[50:51], v[32:35], off offset:256
	s_nop 1
	v_mul_f32_e32 v32, v37, v37
	v_mul_f32_e32 v33, v39, v39
	v_fmac_f32_e32 v32, v36, v36
	v_fmac_f32_e32 v33, v38, v38
	v_add_f32_e32 v32, v32, v33
	v_mul_f32_e32 v33, v43, v43
	v_fmac_f32_e32 v33, v42, v42
	v_add_f32_e32 v32, v33, v32
	v_mul_f32_e32 v33, v41, v41
	v_fmac_f32_e32 v33, v40, v40
	v_add_f32_e32 v32, v33, v32
	v_add_f32_e32 v32, v52, v32
	v_mov_b32_e32 v33, v32
	s_nop 1
	v_permlane16_swap_b32_e32 v32, v33
	s_waitcnt lgkmcnt(0)
	v_add_f32_e32 v32, v32, v33
	v_mov_b32_e32 v33, v32
	s_nop 1
	v_permlane32_swap_b32_e32 v32, v33
	s_and_saveexec_b64 s[26:27], s[4:5]
	s_cbranch_execz .LBB0_712
	v_lshlrev_b64 v[34:35], 6, v[48:49]
	v_lshl_add_u64 v[34:35], s[12:13], 0, v[34:35]
	v_lshl_add_u64 v[34:35], s[24:25], 2, v[34:35]
	s_lshl_b32 s84, s39, 2
	v_lshl_add_u64 v[34:35], v[34:35], 0, s[84:85]
	v_add_f32_e32 v32, v32, v33
	global_store_dword v[34:35], v32, off
; __device__ __forceinline__ unsigned cvtpk(float lo, float hi) { f32x2 v = {lo, hi}; bf16x2_t b = __builtin_convertvector(v, bf16x2_t); return __builtin_bit_cast(unsigned, b); }
;     __device__ __forceinline__ void operator()(const f32x4 (&acc)[2][2][4][2], const Unit& u, int wr, int wc, int fr, int fq) const {
;     ...
;         for (int ai = 0; ai < 2; ++ai)
; #pragma unroll
;             for (int m = 0; m < 4; ++m) {
;                 const int row = u.pm * BM + ai * HALF + wr * 64 + m * 16 + fr;
;                 float ss = 0.f;
; #pragma unroll
;                 for (int bj = 0; bj < 2; ++bj) { const int col = u.pn * BM + bj * HALF + wc * 32 + 8 * fq;
;                     f32x4 v0, v1;
;                     if (xin_p) { const float* xr = (row < MP ? xin_p + (size_t)row * DM : xin_s + (size_t)(row - MP) * DM) + col; v0 = *(const f32x4*)xr; v1 = *(const f32x4*)(xr + 4); }
;                     else { const u32x4 w = *(const u32x4*)(XR + (size_t)row * DM + col);
;                         v0 = (f32x4){__uint_as_float(w.x << 16), __uint_as_float(w.x & 0xffff0000u), __uint_as_float(w.y << 16), __uint_as_float(w.y & 0xffff0000u)};
;                         v1 = (f32x4){__uint_as_float(w.z << 16), __uint_as_float(w.z & 0xffff0000u), __uint_as_float(w.w << 16), __uint_as_float(w.w & 0xffff0000u)}; }
;                     v0 = v0 + acc[ai][bj][m][0]; v1 = v1 + acc[ai][bj][m][1];
;                     if (fout) { *(f32x4*)(fout + (size_t)row * DM + col) = v0; *(f32x4*)(fout + (size_t)row * DM + col + 4) = v1; }
;                     else { u32x4 w; w.x = cvtpk(v0[0], v0[1]); w.y = cvtpk(v0[2], v0[3]); w.z = cvtpk(v1[0], v1[1]); w.w = cvtpk(v1[2], v1[3]); *(u32x4*)(XR + (size_t)row * DM + col) = w; }
;                     if (PS) ss += (v0[0] * v0[0] + v0[1] * v0[1]) + (v0[2] * v0[2] + v0[3] * v0[3]) + (v1[0] * v1[0] + v1[1] * v1[1]) + (v1[2] * v1[2] + v1[3] * v1[3]); }
;                 if (PS) { ss = bfly_add<16>(ss); ss = bfly_add<32>(ss); if (fq == 0) PS[(size_t)row * 16 + 4 * u.pn + wc] = ss; }
.LBB0_712:
	s_or_b64 exec, exec, s[26:27]
	v_add_u32_e32 v32, 0xa0, v140
	v_ashrrev_i32_e32 v33, 31, v32
	v_lshlrev_b64 v[34:35], 11, v[32:33]
	v_lshl_add_u64 v[34:35], s[10:11], 0, v[34:35]
	v_lshl_add_u64 v[34:35], v[138:139], 1, v[34:35]
	s_waitcnt vmcnt(15)
	v_mov_b32_e32 v36, v238
	v_mov_b32_e32 v37, v239
	v_mov_b32_e32 v38, v240
	v_mov_b32_e32 v39, v241
	v_lshlrev_b32_e32 v40, 16, v36
	v_and_b32_e32 v41, 0xffff0000, v36
	v_lshlrev_b32_e32 v36, 16, v37
	v_and_b32_e32 v37, 0xffff0000, v37
	v_lshlrev_b32_e32 v42, 16, v38
	v_and_b32_e32 v43, 0xffff0000, v38
	v_lshlrev_b32_e32 v38, 16, v39
	v_and_b32_e32 v39, 0xffff0000, v39
	v_pk_add_f32 v[30:31], v[30:31], v[36:37]
	v_pk_add_f32 v[28:29], v[28:29], v[40:41]
	v_pk_add_f32 v[36:37], v[26:27], v[38:39]
	v_pk_add_f32 v[38:39], v[24:25], v[42:43]
	v_cvt_pk_bf16_f32 v24, v28, v29
	v_cvt_pk_bf16_f32 v25, v30, v31
	v_cvt_pk_bf16_f32 v26, v38, v39
	v_cvt_pk_bf16_f32 v27, v36, v37
	global_store_dwordx4 v[34:35], v[24:27], off
	s_nop 1
	v_mul_f32_e32 v24, v29, v29
	v_mul_f32_e32 v25, v31, v31
	v_fmac_f32_e32 v24, v28, v28
	v_fmac_f32_e32 v25, v30, v30
	v_add_f32_e32 v24, v24, v25
	v_mul_f32_e32 v25, v39, v39
	v_fmac_f32_e32 v25, v38, v38
	v_add_f32_e32 v24, v25, v24
	v_mul_f32_e32 v25, v37, v37
	v_fmac_f32_e32 v25, v36, v36
	v_add_f32_e32 v36, v25, v24
	s_waitcnt vmcnt(15)
	v_mov_b32_e32 v24, v242
	v_mov_b32_e32 v25, v243
	v_mov_b32_e32 v26, v244
	v_mov_b32_e32 v27, v245
	v_lshlrev_b32_e32 v28, 16, v24
	v_and_b32_e32 v29, 0xffff0000, v24
	v_lshlrev_b32_e32 v24, 16, v25
	v_and_b32_e32 v25, 0xffff0000, v25
	v_lshlrev_b32_e32 v30, 16, v26
	v_and_b32_e32 v31, 0xffff0000, v26
	v_lshlrev_b32_e32 v26, 16, v27
	v_and_b32_e32 v27, 0xffff0000, v27
	v_pk_add_f32 v[22:23], v[22:23], v[24:25]
	v_pk_add_f32 v[20:21], v[20:21], v[28:29]
	v_pk_add_f32 v[24:25], v[18:19], v[26:27]
	v_pk_add_f32 v[26:27], v[16:17], v[30:31]
	v_cvt_pk_bf16_f32 v16, v20, v21
	v_cvt_pk_bf16_f32 v17, v22, v23
	v_cvt_pk_bf16_f32 v18, v26, v27
	v_cvt_pk_bf16_f32 v19, v24, v25
	global_store_dwordx4 v[34:35], v[16:19], off offset:256
	s_nop 1
	v_mul_f32_e32 v16, v21, v21
	v_mul_f32_e32 v17, v23, v23
	v_fmac_f32_e32 v16, v20, v20
	v_fmac_f32_e32 v17, v22, v22
	v_add_f32_e32 v16, v16, v17
	v_mul_f32_e32 v17, v27, v27
	v_fmac_f32_e32 v17, v26, v26
	v_add_f32_e32 v16, v17, v16
	v_mul_f32_e32 v17, v25, v25
	v_fmac_f32_e32 v17, v24, v24
	v_add_f32_e32 v16, v17, v16
	v_add_f32_e32 v16, v36, v16
	v_mov_b32_e32 v17, v16
	s_nop 1
	v_permlane16_swap_b32_e32 v16, v17
	s_waitcnt lgkmcnt(0)
	v_add_f32_e32 v16, v16, v17
	v_mov_b32_e32 v17, v16
	s_nop 1
	v_permlane32_swap_b32_e32 v16, v17
	s_and_saveexec_b64 s[26:27], s[4:5]
	s_cbranch_execz .LBB0_714
	v_lshlrev_b64 v[18:19], 6, v[32:33]
	v_lshl_add_u64 v[18:19], s[12:13], 0, v[18:19]
	v_lshl_add_u64 v[18:19], s[24:25], 2, v[18:19]
	s_lshl_b32 s84, s39, 2
	v_lshl_add_u64 v[18:19], v[18:19], 0, s[84:85]
	v_add_f32_e32 v16, v16, v17
	global_store_dword v[18:19], v16, off
.LBB0_714:
	s_or_b64 exec, exec, s[26:27]
	v_add_u32_e32 v16, 0xb0, v140
	v_ashrrev_i32_e32 v17, 31, v16
	v_lshlrev_b64 v[18:19], 11, v[16:17]
	v_lshl_add_u64 v[18:19], s[10:11], 0, v[18:19]
	v_lshl_add_u64 v[18:19], v[138:139], 1, v[18:19]
	s_waitcnt vmcnt(15)
	v_mov_b32_e32 v20, v246
	v_mov_b32_e32 v21, v247
	v_mov_b32_e32 v22, v248
	v_mov_b32_e32 v23, v249
	v_lshlrev_b32_e32 v24, 16, v20
	v_and_b32_e32 v25, 0xffff0000, v20
	v_lshlrev_b32_e32 v20, 16, v21
	v_and_b32_e32 v21, 0xffff0000, v21
	v_lshlrev_b32_e32 v26, 16, v22
	v_and_b32_e32 v27, 0xffff0000, v22
	v_lshlrev_b32_e32 v22, 16, v23
	v_and_b32_e32 v23, 0xffff0000, v23
	v_pk_add_f32 v[14:15], v[14:15], v[20:21]
	v_pk_add_f32 v[12:13], v[12:13], v[24:25]
	v_pk_add_f32 v[20:21], v[10:11], v[22:23]
	v_pk_add_f32 v[22:23], v[8:9], v[26:27]
	v_cvt_pk_bf16_f32 v8, v12, v13
	v_cvt_pk_bf16_f32 v9, v14, v15
	v_cvt_pk_bf16_f32 v10, v22, v23
	v_cvt_pk_bf16_f32 v11, v20, v21
	global_store_dwordx4 v[18:19], v[8:11], off
	s_nop 1
	v_mul_f32_e32 v8, v13, v13
	v_mul_f32_e32 v9, v15, v15
	v_fmac_f32_e32 v8, v12, v12
	v_fmac_f32_e32 v9, v14, v14
	v_add_f32_e32 v8, v8, v9
	v_mul_f32_e32 v9, v23, v23
	v_fmac_f32_e32 v9, v22, v22
	v_add_f32_e32 v8, v9, v8
	v_mul_f32_e32 v9, v21, v21
	v_fmac_f32_e32 v9, v20, v20
	v_add_f32_e32 v20, v9, v8
	s_waitcnt vmcnt(15)
	v_mov_b32_e32 v8, v250
	v_mov_b32_e32 v9, v251
	v_mov_b32_e32 v10, v252
	v_mov_b32_e32 v11, v253
	v_lshlrev_b32_e32 v12, 16, v8
	v_and_b32_e32 v13, 0xffff0000, v8
	v_lshlrev_b32_e32 v8, 16, v9
	v_and_b32_e32 v9, 0xffff0000, v9
	v_lshlrev_b32_e32 v14, 16, v10
	v_and_b32_e32 v15, 0xffff0000, v10
	v_lshlrev_b32_e32 v10, 16, v11
	v_and_b32_e32 v11, 0xffff0000, v11
	v_pk_add_f32 v[6:7], v[6:7], v[8:9]
	v_pk_add_f32 v[4:5], v[4:5], v[12:13]
	v_pk_add_f32 v[8:9], v[2:3], v[10:11]
	v_pk_add_f32 v[10:11], v[0:1], v[14:15]
	v_cvt_pk_bf16_f32 v0, v4, v5
	v_cvt_pk_bf16_f32 v1, v6, v7
	v_cvt_pk_bf16_f32 v2, v10, v11
	v_cvt_pk_bf16_f32 v3, v8, v9
	global_store_dwordx4 v[18:19], v[0:3], off offset:256
	s_nop 1
	v_mul_f32_e32 v0, v5, v5
	v_mul_f32_e32 v1, v7, v7
	v_fmac_f32_e32 v0, v4, v4
	v_fmac_f32_e32 v1, v6, v6
	v_add_f32_e32 v0, v0, v1
	v_mul_f32_e32 v1, v11, v11
	v_fmac_f32_e32 v1, v10, v10
	v_add_f32_e32 v0, v1, v0
	v_mul_f32_e32 v1, v9, v9
	v_fmac_f32_e32 v1, v8, v8
	v_add_f32_e32 v0, v1, v0
	v_add_f32_e32 v0, v20, v0
	v_mov_b32_e32 v1, v0
	s_nop 1
	v_permlane16_swap_b32_e32 v0, v1
	s_waitcnt lgkmcnt(0)
	v_add_f32_e32 v0, v0, v1
	v_mov_b32_e32 v1, v0
	s_nop 1
	v_permlane32_swap_b32_e32 v0, v1
	s_and_saveexec_b64 s[26:27], s[4:5]
	s_cbranch_execz .LBB0_716
	v_lshlrev_b64 v[2:3], 6, v[16:17]
	v_lshl_add_u64 v[2:3], s[12:13], 0, v[2:3]
	v_lshl_add_u64 v[2:3], s[24:25], 2, v[2:3]
	s_lshl_b32 s84, s39, 2
	v_lshl_add_u64 v[2:3], v[2:3], 0, s[84:85]
	v_add_f32_e32 v0, v0, v1
	global_store_dword v[2:3], v0, off

; __device__ __forceinline__ unsigned cvtpk(float lo, float hi) { f32x2 v = {lo, hi}; bf16x2_t b = __builtin_convertvector(v, bf16x2_t); return __builtin_bit_cast(unsigned, b); }
;     __device__ __forceinline__ void operator()(const f32x4 (&acc)[2][2][4][2], const Unit& u, int wr, int wc, int fr, int fq) const {
;     ...
;                 for (int bj = 0; bj < 2; ++bj) { const int col = u.pn * BM + bj * HALF + wc * 32 + 8 * fq;
;                     f32x4 v0, v1;
;                     if (xin_p) { const float* xr = (row < MP ? xin_p + (size_t)row * DM : xin_s + (size_t)(row - MP) * DM) + col; v0 = *(const f32x4*)xr; v1 = *(const f32x4*)(xr + 4); }
;                     else { const u32x4 w = *(const u32x4*)(XR + (size_t)row * DM + col);
;                         v0 = (f32x4){__uint_as_float(w.x << 16), __uint_as_float(w.x & 0xffff0000u), __uint_as_float(w.y << 16), __uint_as_float(w.y & 0xffff0000u)};
;                         v1 = (f32x4){__uint_as_float(w.z << 16), __uint_as_float(w.z & 0xffff0000u), __uint_as_float(w.w << 16), __uint_as_float(w.w & 0xffff0000u)}; }
;                     v0 = v0 + acc[ai][bj][m][0]; v1 = v1 + acc[ai][bj][m][1];
;                     if (fout) { *(f32x4*)(fout + (size_t)row * DM + col) = v0; *(f32x4*)(fout + (size_t)row * DM + col + 4) = v1; }
;                     else { u32x4 w; w.x = cvtpk(v0[0], v0[1]); w.y = cvtpk(v0[2], v0[3]); w.z = cvtpk(v1[0], v1[1]); w.w = cvtpk(v1[2], v1[3]); *(u32x4*)(XR + (size_t)row * DM + col) = w; }
.LBB0_882:
	v_lshl_add_u32 v140, s45, 8, v154
	v_ashrrev_i32_e32 v141, 31, v140
	v_lshl_or_b32 v138, s44, 8, v156
	v_lshlrev_b64 v[142:143], 11, v[140:141]
	v_lshl_add_u64 v[142:143], s[12:13], 0, v[142:143]
	v_ashrrev_i32_e32 v139, 31, v138
	v_lshl_add_u64 v[142:143], v[138:139], 1, v[142:143]
	v_mov_b32_e32 v166, v142
	v_mov_b32_e32 v167, v143
	s_mov_b64 s[98:99], 0x8000
	s_mov_b64 s[100:101], 0x28000
	global_load_dwordx4 v[190:193], v[166:167], off
	global_load_dwordx4 v[194:197], v[166:167], off offset:256
	v_lshl_add_u64 v[166:167], v[166:167], 0, s[98:99]
	global_load_dwordx4 v[198:201], v[166:167], off
	global_load_dwordx4 v[202:205], v[166:167], off offset:256
	v_lshl_add_u64 v[166:167], v[166:167], 0, s[98:99]
	global_load_dwordx4 v[206:209], v[166:167], off
	global_load_dwordx4 v[210:213], v[166:167], off offset:256
	v_lshl_add_u64 v[166:167], v[166:167], 0, s[98:99]
	global_load_dwordx4 v[214:217], v[166:167], off
	global_load_dwordx4 v[218:221], v[166:167], off offset:256
	v_lshl_add_u64 v[166:167], v[166:167], 0, s[100:101]
	global_load_dwordx4 v[222:225], v[166:167], off
	global_load_dwordx4 v[226:229], v[166:167], off offset:256
	v_lshl_add_u64 v[166:167], v[166:167], 0, s[98:99]
	global_load_dwordx4 v[230:233], v[166:167], off
	global_load_dwordx4 v[234:237], v[166:167], off offset:256
	v_lshl_add_u64 v[166:167], v[166:167], 0, s[98:99]
	global_load_dwordx4 v[238:241], v[166:167], off
	global_load_dwordx4 v[242:245], v[166:167], off offset:256
	v_lshl_add_u64 v[166:167], v[166:167], 0, s[98:99]
	global_load_dwordx4 v[246:249], v[166:167], off
	global_load_dwordx4 v[250:253], v[166:167], off offset:256
	v_cndmask_b32_e64 v152, 0, 1, s[20:21]
	v_cmp_ne_u32_e64 s[6:7], 1, v152
	v_lshlrev_b64 v[152:153], 10, v[140:141]
	s_andn2_b64 vcc, exec, s[20:21]
	v_lshl_add_u64 v[152:153], v[152:153], 2, s[16:17]
	s_waitcnt vmcnt(15)
	v_mov_b32_e32 v158, v190
	v_mov_b32_e32 v159, v191
	v_mov_b32_e32 v160, v192
	v_mov_b32_e32 v161, v193
	v_lshlrev_b32_e32 v162, 16, v158
	v_and_b32_e32 v163, 0xffff0000, v158
	v_lshlrev_b32_e32 v158, 16, v159
	v_and_b32_e32 v159, 0xffff0000, v159
	v_lshlrev_b32_e32 v164, 16, v160
	v_and_b32_e32 v165, 0xffff0000, v160
	v_lshlrev_b32_e32 v160, 16, v161
	v_and_b32_e32 v161, 0xffff0000, v161
	v_pk_add_f32 v[126:127], v[126:127], v[158:159]
	v_pk_add_f32 v[124:125], v[124:125], v[162:163]
	v_pk_add_f32 v[122:123], v[122:123], v[160:161]
	v_pk_add_f32 v[120:121], v[120:121], v[164:165]
	s_cbranch_vccnz .LBB0_965
	v_lshl_add_u64 v[158:159], v[138:139], 2, v[152:153]
	global_store_dwordx4 v[158:159], v[124:127], off
	global_store_dwordx4 v[158:159], v[120:123], off offset:16
	s_cbranch_execnz .LBB0_885

; __device__ __forceinline__ unsigned cvtpk(float lo, float hi) { f32x2 v = {lo, hi}; bf16x2_t b = __builtin_convertvector(v, bf16x2_t); return __builtin_bit_cast(unsigned, b); }
;     __device__ __forceinline__ void operator()(const f32x4 (&acc)[2][2][4][2], const Unit& u, int wr, int wc, int fr, int fq) const {
;     ...
;                 for (int bj = 0; bj < 2; ++bj) { const int col = u.pn * BM + bj * HALF + wc * 32 + 8 * fq;
;                     f32x4 v0, v1;
;                     if (xin_p) { const float* xr = (row < MP ? xin_p + (size_t)row * DM : xin_s + (size_t)(row - MP) * DM) + col; v0 = *(const f32x4*)xr; v1 = *(const f32x4*)(xr + 4); }
;                     else { const u32x4 w = *(const u32x4*)(XR + (size_t)row * DM + col);
;                         v0 = (f32x4){__uint_as_float(w.x << 16), __uint_as_float(w.x & 0xffff0000u), __uint_as_float(w.y << 16), __uint_as_float(w.y & 0xffff0000u)};
;                         v1 = (f32x4){__uint_as_float(w.z << 16), __uint_as_float(w.z & 0xffff0000u), __uint_as_float(w.w << 16), __uint_as_float(w.w & 0xffff0000u)}; }
;                     v0 = v0 + acc[ai][bj][m][0]; v1 = v1 + acc[ai][bj][m][1];
;                     if (fout) { *(f32x4*)(fout + (size_t)row * DM + col) = v0; *(f32x4*)(fout + (size_t)row * DM + col + 4) = v1; }
;                     else { u32x4 w; w.x = cvtpk(v0[0], v0[1]); w.y = cvtpk(v0[2], v0[3]); w.z = cvtpk(v1[0], v1[1]); w.w = cvtpk(v1[2], v1[3]); *(u32x4*)(XR + (size_t)row * DM + col) = w; }
.LBB0_885:
	s_and_b64 vcc, exec, s[6:7]
	s_waitcnt vmcnt(15)
	v_mov_b32_e32 v158, v194
	v_mov_b32_e32 v159, v195
	v_mov_b32_e32 v160, v196
	v_mov_b32_e32 v161, v197
	v_lshlrev_b32_e32 v162, 16, v158
	v_and_b32_e32 v163, 0xffff0000, v158
	v_lshlrev_b32_e32 v158, 16, v159
	v_and_b32_e32 v159, 0xffff0000, v159
	v_lshlrev_b32_e32 v164, 16, v160
	v_and_b32_e32 v165, 0xffff0000, v160
	v_lshlrev_b32_e32 v160, 16, v161
	v_and_b32_e32 v161, 0xffff0000, v161
	v_pk_add_f32 v[118:119], v[118:119], v[158:159]
	v_pk_add_f32 v[116:117], v[116:117], v[162:163]
	v_pk_add_f32 v[114:115], v[114:115], v[160:161]
	v_pk_add_f32 v[112:113], v[112:113], v[164:165]
	s_cbranch_vccnz .LBB0_966
	v_lshl_add_u64 v[152:153], v[138:139], 2, v[152:153]
	global_store_dwordx4 v[152:153], v[116:119], off offset:512
	global_store_dwordx4 v[152:153], v[112:115], off offset:528
	s_cbranch_execnz .LBB0_888

; __device__ __forceinline__ unsigned cvtpk(float lo, float hi) { f32x2 v = {lo, hi}; bf16x2_t b = __builtin_convertvector(v, bf16x2_t); return __builtin_bit_cast(unsigned, b); }
;     __device__ __forceinline__ void operator()(const f32x4 (&acc)[2][2][4][2], const Unit& u, int wr, int wc, int fr, int fq) const {
;     ...
;                 for (int bj = 0; bj < 2; ++bj) { const int col = u.pn * BM + bj * HALF + wc * 32 + 8 * fq;
;                     f32x4 v0, v1;
;                     if (xin_p) { const float* xr = (row < MP ? xin_p + (size_t)row * DM : xin_s + (size_t)(row - MP) * DM) + col; v0 = *(const f32x4*)xr; v1 = *(const f32x4*)(xr + 4); }
;                     else { const u32x4 w = *(const u32x4*)(XR + (size_t)row * DM + col);
;                         v0 = (f32x4){__uint_as_float(w.x << 16), __uint_as_float(w.x & 0xffff0000u), __uint_as_float(w.y << 16), __uint_as_float(w.y & 0xffff0000u)};
;                         v1 = (f32x4){__uint_as_float(w.z << 16), __uint_as_float(w.z & 0xffff0000u), __uint_as_float(w.w << 16), __uint_as_float(w.w & 0xffff0000u)}; }
;                     v0 = v0 + acc[ai][bj][m][0]; v1 = v1 + acc[ai][bj][m][1];
;                     if (fout) { *(f32x4*)(fout + (size_t)row * DM + col) = v0; *(f32x4*)(fout + (size_t)row * DM + col + 4) = v1; }
;                     else { u32x4 w; w.x = cvtpk(v0[0], v0[1]); w.y = cvtpk(v0[2], v0[3]); w.z = cvtpk(v1[0], v1[1]); w.w = cvtpk(v1[2], v1[3]); *(u32x4*)(XR + (size_t)row * DM + col) = w; }
.LBB0_892:
	v_or_b32_e32 v112, 16, v140
	v_ashrrev_i32_e32 v113, 31, v112
	v_lshlrev_b64 v[114:115], 11, v[112:113]
	v_lshl_add_u64 v[114:115], s[12:13], 0, v[114:115]
	v_lshl_add_u64 v[114:115], v[138:139], 1, v[114:115]
	v_lshlrev_b64 v[120:121], 10, v[112:113]
	s_and_b64 vcc, exec, s[6:7]
	s_waitcnt vmcnt(15)
	v_mov_b32_e32 v116, v198
	v_mov_b32_e32 v117, v199
	v_mov_b32_e32 v118, v200
	v_mov_b32_e32 v119, v201
	v_lshlrev_b32_e32 v122, 16, v116
	v_and_b32_e32 v123, 0xffff0000, v116
	v_lshlrev_b32_e32 v116, 16, v117
	v_and_b32_e32 v117, 0xffff0000, v117
	v_lshlrev_b32_e32 v124, 16, v118
	v_and_b32_e32 v125, 0xffff0000, v118
	v_lshlrev_b32_e32 v118, 16, v119
	v_and_b32_e32 v119, 0xffff0000, v119
	v_pk_add_f32 v[110:111], v[110:111], v[116:117]
	v_pk_add_f32 v[108:109], v[108:109], v[122:123]
	v_pk_add_f32 v[106:107], v[106:107], v[118:119]
	v_pk_add_f32 v[104:105], v[104:105], v[124:125]
	v_lshl_add_u64 v[116:117], v[120:121], 2, s[16:17]
	s_cbranch_vccnz .LBB0_967
	v_lshl_add_u64 v[118:119], v[138:139], 2, v[116:117]
	global_store_dwordx4 v[118:119], v[108:111], off
	global_store_dwordx4 v[118:119], v[104:107], off offset:16
	s_cbranch_execnz .LBB0_895

; __device__ __forceinline__ unsigned cvtpk(float lo, float hi) { f32x2 v = {lo, hi}; bf16x2_t b = __builtin_convertvector(v, bf16x2_t); return __builtin_bit_cast(unsigned, b); }
;     __device__ __forceinline__ void operator()(const f32x4 (&acc)[2][2][4][2], const Unit& u, int wr, int wc, int fr, int fq) const {
;     ...
;                 for (int bj = 0; bj < 2; ++bj) { const int col = u.pn * BM + bj * HALF + wc * 32 + 8 * fq;
;                     f32x4 v0, v1;
;                     if (xin_p) { const float* xr = (row < MP ? xin_p + (size_t)row * DM : xin_s + (size_t)(row - MP) * DM) + col; v0 = *(const f32x4*)xr; v1 = *(const f32x4*)(xr + 4); }
;                     else { const u32x4 w = *(const u32x4*)(XR + (size_t)row * DM + col);
;                         v0 = (f32x4){__uint_as_float(w.x << 16), __uint_as_float(w.x & 0xffff0000u), __uint_as_float(w.y << 16), __uint_as_float(w.y & 0xffff0000u)};
;                         v1 = (f32x4){__uint_as_float(w.z << 16), __uint_as_float(w.z & 0xffff0000u), __uint_as_float(w.w << 16), __uint_as_float(w.w & 0xffff0000u)}; }
;                     v0 = v0 + acc[ai][bj][m][0]; v1 = v1 + acc[ai][bj][m][1];
;                     if (fout) { *(f32x4*)(fout + (size_t)row * DM + col) = v0; *(f32x4*)(fout + (size_t)row * DM + col + 4) = v1; }
;                     else { u32x4 w; w.x = cvtpk(v0[0], v0[1]); w.y = cvtpk(v0[2], v0[3]); w.z = cvtpk(v1[0], v1[1]); w.w = cvtpk(v1[2], v1[3]); *(u32x4*)(XR + (size_t)row * DM + col) = w; }
.LBB0_895:
	s_and_b64 vcc, exec, s[6:7]
	s_waitcnt vmcnt(15)
	v_mov_b32_e32 v118, v202
	v_mov_b32_e32 v119, v203
	v_mov_b32_e32 v120, v204
	v_mov_b32_e32 v121, v205
	v_lshlrev_b32_e32 v122, 16, v118
	v_and_b32_e32 v123, 0xffff0000, v118
	v_lshlrev_b32_e32 v118, 16, v119
	v_and_b32_e32 v119, 0xffff0000, v119
	v_lshlrev_b32_e32 v124, 16, v120
	v_and_b32_e32 v125, 0xffff0000, v120
	v_lshlrev_b32_e32 v120, 16, v121
	v_and_b32_e32 v121, 0xffff0000, v121
	v_pk_add_f32 v[102:103], v[102:103], v[118:119]
	v_pk_add_f32 v[100:101], v[100:101], v[122:123]
	v_pk_add_f32 v[98:99], v[98:99], v[120:121]
	v_pk_add_f32 v[96:97], v[96:97], v[124:125]
	s_cbranch_vccnz .LBB0_968
	v_lshl_add_u64 v[116:117], v[138:139], 2, v[116:117]
	global_store_dwordx4 v[116:117], v[100:103], off offset:512
	global_store_dwordx4 v[116:117], v[96:99], off offset:528
	s_cbranch_execnz .LBB0_898

; __device__ __forceinline__ unsigned cvtpk(float lo, float hi) { f32x2 v = {lo, hi}; bf16x2_t b = __builtin_convertvector(v, bf16x2_t); return __builtin_bit_cast(unsigned, b); }
;     __device__ __forceinline__ void operator()(const f32x4 (&acc)[2][2][4][2], const Unit& u, int wr, int wc, int fr, int fq) const {
;     ...
;                 for (int bj = 0; bj < 2; ++bj) { const int col = u.pn * BM + bj * HALF + wc * 32 + 8 * fq;
;                     f32x4 v0, v1;
;                     if (xin_p) { const float* xr = (row < MP ? xin_p + (size_t)row * DM : xin_s + (size_t)(row - MP) * DM) + col; v0 = *(const f32x4*)xr; v1 = *(const f32x4*)(xr + 4); }
;                     else { const u32x4 w = *(const u32x4*)(XR + (size_t)row * DM + col);
;                         v0 = (f32x4){__uint_as_float(w.x << 16), __uint_as_float(w.x & 0xffff0000u), __uint_as_float(w.y << 16), __uint_as_float(w.y & 0xffff0000u)};
;                         v1 = (f32x4){__uint_as_float(w.z << 16), __uint_as_float(w.z & 0xffff0000u), __uint_as_float(w.w << 16), __uint_as_float(w.w & 0xffff0000u)}; }
;                     v0 = v0 + acc[ai][bj][m][0]; v1 = v1 + acc[ai][bj][m][1];
;                     if (fout) { *(f32x4*)(fout + (size_t)row * DM + col) = v0; *(f32x4*)(fout + (size_t)row * DM + col + 4) = v1; }
;                     else { u32x4 w; w.x = cvtpk(v0[0], v0[1]); w.y = cvtpk(v0[2], v0[3]); w.z = cvtpk(v1[0], v1[1]); w.w = cvtpk(v1[2], v1[3]); *(u32x4*)(XR + (size_t)row * DM + col) = w; }
.LBB0_902:
	v_or_b32_e32 v96, 32, v140
	v_ashrrev_i32_e32 v97, 31, v96
	v_lshlrev_b64 v[98:99], 11, v[96:97]
	v_lshl_add_u64 v[98:99], s[12:13], 0, v[98:99]
	v_lshl_add_u64 v[98:99], v[138:139], 1, v[98:99]
	v_lshlrev_b64 v[104:105], 10, v[96:97]
	s_and_b64 vcc, exec, s[6:7]
	s_waitcnt vmcnt(15)
	v_mov_b32_e32 v100, v206
	v_mov_b32_e32 v101, v207
	v_mov_b32_e32 v102, v208
	v_mov_b32_e32 v103, v209
	v_lshlrev_b32_e32 v106, 16, v100
	v_and_b32_e32 v107, 0xffff0000, v100
	v_lshlrev_b32_e32 v100, 16, v101
	v_and_b32_e32 v101, 0xffff0000, v101
	v_lshlrev_b32_e32 v108, 16, v102
	v_and_b32_e32 v109, 0xffff0000, v102
	v_lshlrev_b32_e32 v102, 16, v103
	v_and_b32_e32 v103, 0xffff0000, v103
	v_pk_add_f32 v[94:95], v[94:95], v[100:101]
	v_pk_add_f32 v[92:93], v[92:93], v[106:107]
	v_pk_add_f32 v[90:91], v[90:91], v[102:103]
	v_pk_add_f32 v[88:89], v[88:89], v[108:109]
	v_lshl_add_u64 v[100:101], v[104:105], 2, s[16:17]
	s_cbranch_vccnz .LBB0_969
	v_lshl_add_u64 v[102:103], v[138:139], 2, v[100:101]
	global_store_dwordx4 v[102:103], v[92:95], off
	global_store_dwordx4 v[102:103], v[88:91], off offset:16
	s_cbranch_execnz .LBB0_905

; __device__ __forceinline__ unsigned cvtpk(float lo, float hi) { f32x2 v = {lo, hi}; bf16x2_t b = __builtin_convertvector(v, bf16x2_t); return __builtin_bit_cast(unsigned, b); }
;     __device__ __forceinline__ void operator()(const f32x4 (&acc)[2][2][4][2], const Unit& u, int wr, int wc, int fr, int fq) const {
;     ...
;                 for (int bj = 0; bj < 2; ++bj) { const int col = u.pn * BM + bj * HALF + wc * 32 + 8 * fq;
;                     f32x4 v0, v1;
;                     if (xin_p) { const float* xr = (row < MP ? xin_p + (size_t)row * DM : xin_s + (size_t)(row - MP) * DM) + col; v0 = *(const f32x4*)xr; v1 = *(const f32x4*)(xr + 4); }
;                     else { const u32x4 w = *(const u32x4*)(XR + (size_t)row * DM + col);
;                         v0 = (f32x4){__uint_as_float(w.x << 16), __uint_as_float(w.x & 0xffff0000u), __uint_as_float(w.y << 16), __uint_as_float(w.y & 0xffff0000u)};
;                         v1 = (f32x4){__uint_as_float(w.z << 16), __uint_as_float(w.z & 0xffff0000u), __uint_as_float(w.w << 16), __uint_as_float(w.w & 0xffff0000u)}; }
;                     v0 = v0 + acc[ai][bj][m][0]; v1 = v1 + acc[ai][bj][m][1];
;                     if (fout) { *(f32x4*)(fout + (size_t)row * DM + col) = v0; *(f32x4*)(fout + (size_t)row * DM + col + 4) = v1; }
;                     else { u32x4 w; w.x = cvtpk(v0[0], v0[1]); w.y = cvtpk(v0[2], v0[3]); w.z = cvtpk(v1[0], v1[1]); w.w = cvtpk(v1[2], v1[3]); *(u32x4*)(XR + (size_t)row * DM + col) = w; }
.LBB0_905:
	s_and_b64 vcc, exec, s[6:7]
	s_waitcnt vmcnt(15)
	v_mov_b32_e32 v102, v210
	v_mov_b32_e32 v103, v211
	v_mov_b32_e32 v104, v212
	v_mov_b32_e32 v105, v213
	v_lshlrev_b32_e32 v106, 16, v102
	v_and_b32_e32 v107, 0xffff0000, v102
	v_lshlrev_b32_e32 v102, 16, v103
	v_and_b32_e32 v103, 0xffff0000, v103
	v_lshlrev_b32_e32 v108, 16, v104
	v_and_b32_e32 v109, 0xffff0000, v104
	v_lshlrev_b32_e32 v104, 16, v105
	v_and_b32_e32 v105, 0xffff0000, v105
	v_pk_add_f32 v[86:87], v[86:87], v[102:103]
	v_pk_add_f32 v[84:85], v[84:85], v[106:107]
	v_pk_add_f32 v[82:83], v[82:83], v[104:105]
	v_pk_add_f32 v[80:81], v[80:81], v[108:109]
	s_cbranch_vccnz .LBB0_970
	v_lshl_add_u64 v[100:101], v[138:139], 2, v[100:101]
	global_store_dwordx4 v[100:101], v[84:87], off offset:512
	global_store_dwordx4 v[100:101], v[80:83], off offset:528
	s_cbranch_execnz .LBB0_908

; __device__ __forceinline__ unsigned cvtpk(float lo, float hi) { f32x2 v = {lo, hi}; bf16x2_t b = __builtin_convertvector(v, bf16x2_t); return __builtin_bit_cast(unsigned, b); }
;     __device__ __forceinline__ void operator()(const f32x4 (&acc)[2][2][4][2], const Unit& u, int wr, int wc, int fr, int fq) const {
;     ...
;                 for (int bj = 0; bj < 2; ++bj) { const int col = u.pn * BM + bj * HALF + wc * 32 + 8 * fq;
;                     f32x4 v0, v1;
;                     if (xin_p) { const float* xr = (row < MP ? xin_p + (size_t)row * DM : xin_s + (size_t)(row - MP) * DM) + col; v0 = *(const f32x4*)xr; v1 = *(const f32x4*)(xr + 4); }
;                     else { const u32x4 w = *(const u32x4*)(XR + (size_t)row * DM + col);
;                         v0 = (f32x4){__uint_as_float(w.x << 16), __uint_as_float(w.x & 0xffff0000u), __uint_as_float(w.y << 16), __uint_as_float(w.y & 0xffff0000u)};
;                         v1 = (f32x4){__uint_as_float(w.z << 16), __uint_as_float(w.z & 0xffff0000u), __uint_as_float(w.w << 16), __uint_as_float(w.w & 0xffff0000u)}; }
;                     v0 = v0 + acc[ai][bj][m][0]; v1 = v1 + acc[ai][bj][m][1];
;                     if (fout) { *(f32x4*)(fout + (size_t)row * DM + col) = v0; *(f32x4*)(fout + (size_t)row * DM + col + 4) = v1; }
;                     else { u32x4 w; w.x = cvtpk(v0[0], v0[1]); w.y = cvtpk(v0[2], v0[3]); w.z = cvtpk(v1[0], v1[1]); w.w = cvtpk(v1[2], v1[3]); *(u32x4*)(XR + (size_t)row * DM + col) = w; }
.LBB0_912:
	v_or_b32_e32 v80, 48, v140
	v_ashrrev_i32_e32 v81, 31, v80
	v_lshlrev_b64 v[82:83], 11, v[80:81]
	v_lshl_add_u64 v[82:83], s[12:13], 0, v[82:83]
	v_lshl_add_u64 v[82:83], v[138:139], 1, v[82:83]
	v_lshlrev_b64 v[88:89], 10, v[80:81]
	s_and_b64 vcc, exec, s[6:7]
	s_waitcnt vmcnt(15)
	v_mov_b32_e32 v84, v214
	v_mov_b32_e32 v85, v215
	v_mov_b32_e32 v86, v216
	v_mov_b32_e32 v87, v217
	v_lshlrev_b32_e32 v90, 16, v84
	v_and_b32_e32 v91, 0xffff0000, v84
	v_lshlrev_b32_e32 v84, 16, v85
	v_and_b32_e32 v85, 0xffff0000, v85
	v_lshlrev_b32_e32 v92, 16, v86
	v_and_b32_e32 v93, 0xffff0000, v86
	v_lshlrev_b32_e32 v86, 16, v87
	v_and_b32_e32 v87, 0xffff0000, v87
	v_pk_add_f32 v[78:79], v[78:79], v[84:85]
	v_pk_add_f32 v[76:77], v[76:77], v[90:91]
	v_pk_add_f32 v[74:75], v[74:75], v[86:87]
	v_pk_add_f32 v[72:73], v[72:73], v[92:93]
	v_lshl_add_u64 v[84:85], v[88:89], 2, s[16:17]
	s_cbranch_vccnz .LBB0_971
	v_lshl_add_u64 v[86:87], v[138:139], 2, v[84:85]
	global_store_dwordx4 v[86:87], v[76:79], off
	global_store_dwordx4 v[86:87], v[72:75], off offset:16
	s_cbranch_execnz .LBB0_915

; __device__ __forceinline__ unsigned cvtpk(float lo, float hi) { f32x2 v = {lo, hi}; bf16x2_t b = __builtin_convertvector(v, bf16x2_t); return __builtin_bit_cast(unsigned, b); }
;     __device__ __forceinline__ void operator()(const f32x4 (&acc)[2][2][4][2], const Unit& u, int wr, int wc, int fr, int fq) const {
;     ...
;                 for (int bj = 0; bj < 2; ++bj) { const int col = u.pn * BM + bj * HALF + wc * 32 + 8 * fq;
;                     f32x4 v0, v1;
;                     if (xin_p) { const float* xr = (row < MP ? xin_p + (size_t)row * DM : xin_s + (size_t)(row - MP) * DM) + col; v0 = *(const f32x4*)xr; v1 = *(const f32x4*)(xr + 4); }
;                     else { const u32x4 w = *(const u32x4*)(XR + (size_t)row * DM + col);
;                         v0 = (f32x4){__uint_as_float(w.x << 16), __uint_as_float(w.x & 0xffff0000u), __uint_as_float(w.y << 16), __uint_as_float(w.y & 0xffff0000u)};
;                         v1 = (f32x4){__uint_as_float(w.z << 16), __uint_as_float(w.z & 0xffff0000u), __uint_as_float(w.w << 16), __uint_as_float(w.w & 0xffff0000u)}; }
;                     v0 = v0 + acc[ai][bj][m][0]; v1 = v1 + acc[ai][bj][m][1];
;                     if (fout) { *(f32x4*)(fout + (size_t)row * DM + col) = v0; *(f32x4*)(fout + (size_t)row * DM + col + 4) = v1; }
;                     else { u32x4 w; w.x = cvtpk(v0[0], v0[1]); w.y = cvtpk(v0[2], v0[3]); w.z = cvtpk(v1[0], v1[1]); w.w = cvtpk(v1[2], v1[3]); *(u32x4*)(XR + (size_t)row * DM + col) = w; }
.LBB0_915:
	s_and_b64 vcc, exec, s[6:7]
	s_waitcnt vmcnt(15)
	v_mov_b32_e32 v86, v218
	v_mov_b32_e32 v87, v219
	v_mov_b32_e32 v88, v220
	v_mov_b32_e32 v89, v221
	v_lshlrev_b32_e32 v90, 16, v86
	v_and_b32_e32 v91, 0xffff0000, v86
	v_lshlrev_b32_e32 v86, 16, v87
	v_and_b32_e32 v87, 0xffff0000, v87
	v_lshlrev_b32_e32 v92, 16, v88
	v_and_b32_e32 v93, 0xffff0000, v88
	v_lshlrev_b32_e32 v88, 16, v89
	v_and_b32_e32 v89, 0xffff0000, v89
	v_pk_add_f32 v[70:71], v[70:71], v[86:87]
	v_pk_add_f32 v[68:69], v[68:69], v[90:91]
	v_pk_add_f32 v[66:67], v[66:67], v[88:89]
	v_pk_add_f32 v[64:65], v[64:65], v[92:93]
	s_cbranch_vccnz .LBB0_972
	v_lshl_add_u64 v[84:85], v[138:139], 2, v[84:85]
	global_store_dwordx4 v[84:85], v[68:71], off offset:512
	global_store_dwordx4 v[84:85], v[64:67], off offset:528
	s_cbranch_execnz .LBB0_918

; __device__ __forceinline__ unsigned cvtpk(float lo, float hi) { f32x2 v = {lo, hi}; bf16x2_t b = __builtin_convertvector(v, bf16x2_t); return __builtin_bit_cast(unsigned, b); }
;     __device__ __forceinline__ void operator()(const f32x4 (&acc)[2][2][4][2], const Unit& u, int wr, int wc, int fr, int fq) const {
;     ...
;                 for (int bj = 0; bj < 2; ++bj) { const int col = u.pn * BM + bj * HALF + wc * 32 + 8 * fq;
;                     f32x4 v0, v1;
;                     if (xin_p) { const float* xr = (row < MP ? xin_p + (size_t)row * DM : xin_s + (size_t)(row - MP) * DM) + col; v0 = *(const f32x4*)xr; v1 = *(const f32x4*)(xr + 4); }
;                     else { const u32x4 w = *(const u32x4*)(XR + (size_t)row * DM + col);
;                         v0 = (f32x4){__uint_as_float(w.x << 16), __uint_as_float(w.x & 0xffff0000u), __uint_as_float(w.y << 16), __uint_as_float(w.y & 0xffff0000u)};
;                         v1 = (f32x4){__uint_as_float(w.z << 16), __uint_as_float(w.z & 0xffff0000u), __uint_as_float(w.w << 16), __uint_as_float(w.w & 0xffff0000u)}; }
;                     v0 = v0 + acc[ai][bj][m][0]; v1 = v1 + acc[ai][bj][m][1];
;                     if (fout) { *(f32x4*)(fout + (size_t)row * DM + col) = v0; *(f32x4*)(fout + (size_t)row * DM + col + 4) = v1; }
;                     else { u32x4 w; w.x = cvtpk(v0[0], v0[1]); w.y = cvtpk(v0[2], v0[3]); w.z = cvtpk(v1[0], v1[1]); w.w = cvtpk(v1[2], v1[3]); *(u32x4*)(XR + (size_t)row * DM + col) = w; }
.LBB0_922:
	v_add_u32_e32 v64, 0x80, v140
	v_ashrrev_i32_e32 v65, 31, v64
	v_lshlrev_b64 v[66:67], 11, v[64:65]
	v_lshl_add_u64 v[66:67], s[12:13], 0, v[66:67]
	v_lshl_add_u64 v[66:67], v[138:139], 1, v[66:67]
	v_lshlrev_b64 v[72:73], 10, v[64:65]
	s_and_b64 vcc, exec, s[6:7]
	s_waitcnt vmcnt(15)
	v_mov_b32_e32 v68, v222
	v_mov_b32_e32 v69, v223
	v_mov_b32_e32 v70, v224
	v_mov_b32_e32 v71, v225
	v_lshlrev_b32_e32 v74, 16, v68
	v_and_b32_e32 v75, 0xffff0000, v68
	v_lshlrev_b32_e32 v68, 16, v69
	v_and_b32_e32 v69, 0xffff0000, v69
	v_lshlrev_b32_e32 v76, 16, v70
	v_and_b32_e32 v77, 0xffff0000, v70
	v_lshlrev_b32_e32 v70, 16, v71
	v_and_b32_e32 v71, 0xffff0000, v71
	v_pk_add_f32 v[62:63], v[62:63], v[68:69]
	v_pk_add_f32 v[60:61], v[60:61], v[74:75]
	v_pk_add_f32 v[58:59], v[58:59], v[70:71]
	v_pk_add_f32 v[56:57], v[56:57], v[76:77]
	v_lshl_add_u64 v[68:69], v[72:73], 2, s[16:17]
	s_cbranch_vccnz .LBB0_973
	v_lshl_add_u64 v[70:71], v[138:139], 2, v[68:69]
	global_store_dwordx4 v[70:71], v[60:63], off
	global_store_dwordx4 v[70:71], v[56:59], off offset:16
	s_cbranch_execnz .LBB0_925

; __device__ __forceinline__ unsigned cvtpk(float lo, float hi) { f32x2 v = {lo, hi}; bf16x2_t b = __builtin_convertvector(v, bf16x2_t); return __builtin_bit_cast(unsigned, b); }
;     __device__ __forceinline__ void operator()(const f32x4 (&acc)[2][2][4][2], const Unit& u, int wr, int wc, int fr, int fq) const {
;     ...
;                 for (int bj = 0; bj < 2; ++bj) { const int col = u.pn * BM + bj * HALF + wc * 32 + 8 * fq;
;                     f32x4 v0, v1;
;                     if (xin_p) { const float* xr = (row < MP ? xin_p + (size_t)row * DM : xin_s + (size_t)(row - MP) * DM) + col; v0 = *(const f32x4*)xr; v1 = *(const f32x4*)(xr + 4); }
;                     else { const u32x4 w = *(const u32x4*)(XR + (size_t)row * DM + col);
;                         v0 = (f32x4){__uint_as_float(w.x << 16), __uint_as_float(w.x & 0xffff0000u), __uint_as_float(w.y << 16), __uint_as_float(w.y & 0xffff0000u)};
;                         v1 = (f32x4){__uint_as_float(w.z << 16), __uint_as_float(w.z & 0xffff0000u), __uint_as_float(w.w << 16), __uint_as_float(w.w & 0xffff0000u)}; }
;                     v0 = v0 + acc[ai][bj][m][0]; v1 = v1 + acc[ai][bj][m][1];
;                     if (fout) { *(f32x4*)(fout + (size_t)row * DM + col) = v0; *(f32x4*)(fout + (size_t)row * DM + col + 4) = v1; }
;                     else { u32x4 w; w.x = cvtpk(v0[0], v0[1]); w.y = cvtpk(v0[2], v0[3]); w.z = cvtpk(v1[0], v1[1]); w.w = cvtpk(v1[2], v1[3]); *(u32x4*)(XR + (size_t)row * DM + col) = w; }
.LBB0_925:
	s_and_b64 vcc, exec, s[6:7]
	s_waitcnt vmcnt(15)
	v_mov_b32_e32 v70, v226
	v_mov_b32_e32 v71, v227
	v_mov_b32_e32 v72, v228
	v_mov_b32_e32 v73, v229
	v_lshlrev_b32_e32 v74, 16, v70
	v_and_b32_e32 v75, 0xffff0000, v70
	v_lshlrev_b32_e32 v70, 16, v71
	v_and_b32_e32 v71, 0xffff0000, v71
	v_lshlrev_b32_e32 v76, 16, v72
	v_and_b32_e32 v77, 0xffff0000, v72
	v_lshlrev_b32_e32 v72, 16, v73
	v_and_b32_e32 v73, 0xffff0000, v73
	v_pk_add_f32 v[54:55], v[54:55], v[70:71]
	v_pk_add_f32 v[52:53], v[52:53], v[74:75]
	v_pk_add_f32 v[50:51], v[50:51], v[72:73]
	v_pk_add_f32 v[48:49], v[48:49], v[76:77]
	s_cbranch_vccnz .LBB0_974
	v_lshl_add_u64 v[68:69], v[138:139], 2, v[68:69]
	global_store_dwordx4 v[68:69], v[52:55], off offset:512
	global_store_dwordx4 v[68:69], v[48:51], off offset:528
	s_cbranch_execnz .LBB0_928

; __device__ __forceinline__ unsigned cvtpk(float lo, float hi) { f32x2 v = {lo, hi}; bf16x2_t b = __builtin_convertvector(v, bf16x2_t); return __builtin_bit_cast(unsigned, b); }
;     __device__ __forceinline__ void operator()(const f32x4 (&acc)[2][2][4][2], const Unit& u, int wr, int wc, int fr, int fq) const {
;     ...
;                 for (int bj = 0; bj < 2; ++bj) { const int col = u.pn * BM + bj * HALF + wc * 32 + 8 * fq;
;                     f32x4 v0, v1;
;                     if (xin_p) { const float* xr = (row < MP ? xin_p + (size_t)row * DM : xin_s + (size_t)(row - MP) * DM) + col; v0 = *(const f32x4*)xr; v1 = *(const f32x4*)(xr + 4); }
;                     else { const u32x4 w = *(const u32x4*)(XR + (size_t)row * DM + col);
;                         v0 = (f32x4){__uint_as_float(w.x << 16), __uint_as_float(w.x & 0xffff0000u), __uint_as_float(w.y << 16), __uint_as_float(w.y & 0xffff0000u)};
;                         v1 = (f32x4){__uint_as_float(w.z << 16), __uint_as_float(w.z & 0xffff0000u), __uint_as_float(w.w << 16), __uint_as_float(w.w & 0xffff0000u)}; }
;                     v0 = v0 + acc[ai][bj][m][0]; v1 = v1 + acc[ai][bj][m][1];
;                     if (fout) { *(f32x4*)(fout + (size_t)row * DM + col) = v0; *(f32x4*)(fout + (size_t)row * DM + col + 4) = v1; }
;                     else { u32x4 w; w.x = cvtpk(v0[0], v0[1]); w.y = cvtpk(v0[2], v0[3]); w.z = cvtpk(v1[0], v1[1]); w.w = cvtpk(v1[2], v1[3]); *(u32x4*)(XR + (size_t)row * DM + col) = w; }
.LBB0_932:
	v_add_u32_e32 v48, 0x90, v140
	v_ashrrev_i32_e32 v49, 31, v48
	v_lshlrev_b64 v[50:51], 11, v[48:49]
	v_lshl_add_u64 v[50:51], s[12:13], 0, v[50:51]
	v_lshl_add_u64 v[50:51], v[138:139], 1, v[50:51]
	v_lshlrev_b64 v[56:57], 10, v[48:49]
	s_and_b64 vcc, exec, s[6:7]
	s_waitcnt vmcnt(15)
	v_mov_b32_e32 v52, v230
	v_mov_b32_e32 v53, v231
	v_mov_b32_e32 v54, v232
	v_mov_b32_e32 v55, v233
	v_lshlrev_b32_e32 v58, 16, v52
	v_and_b32_e32 v59, 0xffff0000, v52
	v_lshlrev_b32_e32 v52, 16, v53
	v_and_b32_e32 v53, 0xffff0000, v53
	v_lshlrev_b32_e32 v60, 16, v54
	v_and_b32_e32 v61, 0xffff0000, v54
	v_lshlrev_b32_e32 v54, 16, v55
	v_and_b32_e32 v55, 0xffff0000, v55
	v_pk_add_f32 v[46:47], v[46:47], v[52:53]
	v_pk_add_f32 v[44:45], v[44:45], v[58:59]
	v_pk_add_f32 v[42:43], v[42:43], v[54:55]
	v_pk_add_f32 v[40:41], v[40:41], v[60:61]
	v_lshl_add_u64 v[52:53], v[56:57], 2, s[16:17]
	s_cbranch_vccnz .LBB0_975
	v_lshl_add_u64 v[54:55], v[138:139], 2, v[52:53]
	global_store_dwordx4 v[54:55], v[44:47], off
	global_store_dwordx4 v[54:55], v[40:43], off offset:16
	s_cbranch_execnz .LBB0_935

; __device__ __forceinline__ unsigned cvtpk(float lo, float hi) { f32x2 v = {lo, hi}; bf16x2_t b = __builtin_convertvector(v, bf16x2_t); return __builtin_bit_cast(unsigned, b); }
;     __device__ __forceinline__ void operator()(const f32x4 (&acc)[2][2][4][2], const Unit& u, int wr, int wc, int fr, int fq) const {
;     ...
;                 for (int bj = 0; bj < 2; ++bj) { const int col = u.pn * BM + bj * HALF + wc * 32 + 8 * fq;
;                     f32x4 v0, v1;
;                     if (xin_p) { const float* xr = (row < MP ? xin_p + (size_t)row * DM : xin_s + (size_t)(row - MP) * DM) + col; v0 = *(const f32x4*)xr; v1 = *(const f32x4*)(xr + 4); }
;                     else { const u32x4 w = *(const u32x4*)(XR + (size_t)row * DM + col);
;                         v0 = (f32x4){__uint_as_float(w.x << 16), __uint_as_float(w.x & 0xffff0000u), __uint_as_float(w.y << 16), __uint_as_float(w.y & 0xffff0000u)};
;                         v1 = (f32x4){__uint_as_float(w.z << 16), __uint_as_float(w.z & 0xffff0000u), __uint_as_float(w.w << 16), __uint_as_float(w.w & 0xffff0000u)}; }
;                     v0 = v0 + acc[ai][bj][m][0]; v1 = v1 + acc[ai][bj][m][1];
;                     if (fout) { *(f32x4*)(fout + (size_t)row * DM + col) = v0; *(f32x4*)(fout + (size_t)row * DM + col + 4) = v1; }
;                     else { u32x4 w; w.x = cvtpk(v0[0], v0[1]); w.y = cvtpk(v0[2], v0[3]); w.z = cvtpk(v1[0], v1[1]); w.w = cvtpk(v1[2], v1[3]); *(u32x4*)(XR + (size_t)row * DM + col) = w; }
.LBB0_935:
	s_and_b64 vcc, exec, s[6:7]
	s_waitcnt vmcnt(15)
	v_mov_b32_e32 v54, v234
	v_mov_b32_e32 v55, v235
	v_mov_b32_e32 v56, v236
	v_mov_b32_e32 v57, v237
	v_lshlrev_b32_e32 v58, 16, v54
	v_and_b32_e32 v59, 0xffff0000, v54
	v_lshlrev_b32_e32 v54, 16, v55
	v_and_b32_e32 v55, 0xffff0000, v55
	v_lshlrev_b32_e32 v60, 16, v56
	v_and_b32_e32 v61, 0xffff0000, v56
	v_lshlrev_b32_e32 v56, 16, v57
	v_and_b32_e32 v57, 0xffff0000, v57
	v_pk_add_f32 v[38:39], v[38:39], v[54:55]
	v_pk_add_f32 v[36:37], v[36:37], v[58:59]
	v_pk_add_f32 v[34:35], v[34:35], v[56:57]
	v_pk_add_f32 v[32:33], v[32:33], v[60:61]
	s_cbranch_vccnz .LBB0_976
	v_lshl_add_u64 v[52:53], v[138:139], 2, v[52:53]
	global_store_dwordx4 v[52:53], v[36:39], off offset:512
	global_store_dwordx4 v[52:53], v[32:35], off offset:528
	s_cbranch_execnz .LBB0_938

; __device__ __forceinline__ unsigned cvtpk(float lo, float hi) { f32x2 v = {lo, hi}; bf16x2_t b = __builtin_convertvector(v, bf16x2_t); return __builtin_bit_cast(unsigned, b); }
;     __device__ __forceinline__ void operator()(const f32x4 (&acc)[2][2][4][2], const Unit& u, int wr, int wc, int fr, int fq) const {
;     ...
;                 for (int bj = 0; bj < 2; ++bj) { const int col = u.pn * BM + bj * HALF + wc * 32 + 8 * fq;
;                     f32x4 v0, v1;
;                     if (xin_p) { const float* xr = (row < MP ? xin_p + (size_t)row * DM : xin_s + (size_t)(row - MP) * DM) + col; v0 = *(const f32x4*)xr; v1 = *(const f32x4*)(xr + 4); }
;                     else { const u32x4 w = *(const u32x4*)(XR + (size_t)row * DM + col);
;                         v0 = (f32x4){__uint_as_float(w.x << 16), __uint_as_float(w.x & 0xffff0000u), __uint_as_float(w.y << 16), __uint_as_float(w.y & 0xffff0000u)};
;                         v1 = (f32x4){__uint_as_float(w.z << 16), __uint_as_float(w.z & 0xffff0000u), __uint_as_float(w.w << 16), __uint_as_float(w.w & 0xffff0000u)}; }
;                     v0 = v0 + acc[ai][bj][m][0]; v1 = v1 + acc[ai][bj][m][1];
;                     if (fout) { *(f32x4*)(fout + (size_t)row * DM + col) = v0; *(f32x4*)(fout + (size_t)row * DM + col + 4) = v1; }
;                     else { u32x4 w; w.x = cvtpk(v0[0], v0[1]); w.y = cvtpk(v0[2], v0[3]); w.z = cvtpk(v1[0], v1[1]); w.w = cvtpk(v1[2], v1[3]); *(u32x4*)(XR + (size_t)row * DM + col) = w; }
.LBB0_942:
	v_add_u32_e32 v32, 0xa0, v140
	v_ashrrev_i32_e32 v33, 31, v32
	v_lshlrev_b64 v[34:35], 11, v[32:33]
	v_lshl_add_u64 v[34:35], s[12:13], 0, v[34:35]
	v_lshl_add_u64 v[34:35], v[138:139], 1, v[34:35]
	v_lshlrev_b64 v[40:41], 10, v[32:33]
	s_and_b64 vcc, exec, s[6:7]
	s_waitcnt vmcnt(15)
	v_mov_b32_e32 v36, v238
	v_mov_b32_e32 v37, v239
	v_mov_b32_e32 v38, v240
	v_mov_b32_e32 v39, v241
	v_lshlrev_b32_e32 v42, 16, v36
	v_and_b32_e32 v43, 0xffff0000, v36
	v_lshlrev_b32_e32 v36, 16, v37
	v_and_b32_e32 v37, 0xffff0000, v37
	v_lshlrev_b32_e32 v44, 16, v38
	v_and_b32_e32 v45, 0xffff0000, v38
	v_lshlrev_b32_e32 v38, 16, v39
	v_and_b32_e32 v39, 0xffff0000, v39
	v_pk_add_f32 v[30:31], v[30:31], v[36:37]
	v_pk_add_f32 v[28:29], v[28:29], v[42:43]
	v_pk_add_f32 v[26:27], v[26:27], v[38:39]
	v_pk_add_f32 v[24:25], v[24:25], v[44:45]
	v_lshl_add_u64 v[36:37], v[40:41], 2, s[16:17]
	s_cbranch_vccnz .LBB0_977
	v_lshl_add_u64 v[38:39], v[138:139], 2, v[36:37]
	global_store_dwordx4 v[38:39], v[28:31], off
	global_store_dwordx4 v[38:39], v[24:27], off offset:16
	s_cbranch_execnz .LBB0_945

; __device__ __forceinline__ unsigned cvtpk(float lo, float hi) { f32x2 v = {lo, hi}; bf16x2_t b = __builtin_convertvector(v, bf16x2_t); return __builtin_bit_cast(unsigned, b); }
;     __device__ __forceinline__ void operator()(const f32x4 (&acc)[2][2][4][2], const Unit& u, int wr, int wc, int fr, int fq) const {
;     ...
;                 for (int bj = 0; bj < 2; ++bj) { const int col = u.pn * BM + bj * HALF + wc * 32 + 8 * fq;
;                     f32x4 v0, v1;
;                     if (xin_p) { const float* xr = (row < MP ? xin_p + (size_t)row * DM : xin_s + (size_t)(row - MP) * DM) + col; v0 = *(const f32x4*)xr; v1 = *(const f32x4*)(xr + 4); }
;                     else { const u32x4 w = *(const u32x4*)(XR + (size_t)row * DM + col);
;                         v0 = (f32x4){__uint_as_float(w.x << 16), __uint_as_float(w.x & 0xffff0000u), __uint_as_float(w.y << 16), __uint_as_float(w.y & 0xffff0000u)};
;                         v1 = (f32x4){__uint_as_float(w.z << 16), __uint_as_float(w.z & 0xffff0000u), __uint_as_float(w.w << 16), __uint_as_float(w.w & 0xffff0000u)}; }
;                     v0 = v0 + acc[ai][bj][m][0]; v1 = v1 + acc[ai][bj][m][1];
;                     if (fout) { *(f32x4*)(fout + (size_t)row * DM + col) = v0; *(f32x4*)(fout + (size_t)row * DM + col + 4) = v1; }
;                     else { u32x4 w; w.x = cvtpk(v0[0], v0[1]); w.y = cvtpk(v0[2], v0[3]); w.z = cvtpk(v1[0], v1[1]); w.w = cvtpk(v1[2], v1[3]); *(u32x4*)(XR + (size_t)row * DM + col) = w; }
.LBB0_945:
	s_and_b64 vcc, exec, s[6:7]
	s_waitcnt vmcnt(15)
	v_mov_b32_e32 v38, v242
	v_mov_b32_e32 v39, v243
	v_mov_b32_e32 v40, v244
	v_mov_b32_e32 v41, v245
	v_lshlrev_b32_e32 v42, 16, v38
	v_and_b32_e32 v43, 0xffff0000, v38
	v_lshlrev_b32_e32 v38, 16, v39
	v_and_b32_e32 v39, 0xffff0000, v39
	v_lshlrev_b32_e32 v44, 16, v40
	v_and_b32_e32 v45, 0xffff0000, v40
	v_lshlrev_b32_e32 v40, 16, v41
	v_and_b32_e32 v41, 0xffff0000, v41
	v_pk_add_f32 v[22:23], v[22:23], v[38:39]
	v_pk_add_f32 v[20:21], v[20:21], v[42:43]
	v_pk_add_f32 v[18:19], v[18:19], v[40:41]
	v_pk_add_f32 v[16:17], v[16:17], v[44:45]
	s_cbranch_vccnz .LBB0_978
	v_lshl_add_u64 v[36:37], v[138:139], 2, v[36:37]
	global_store_dwordx4 v[36:37], v[20:23], off offset:512
	global_store_dwordx4 v[36:37], v[16:19], off offset:528
	s_cbranch_execnz .LBB0_948

; __device__ __forceinline__ unsigned cvtpk(float lo, float hi) { f32x2 v = {lo, hi}; bf16x2_t b = __builtin_convertvector(v, bf16x2_t); return __builtin_bit_cast(unsigned, b); }
;     __device__ __forceinline__ void operator()(const f32x4 (&acc)[2][2][4][2], const Unit& u, int wr, int wc, int fr, int fq) const {
;     ...
;                 for (int bj = 0; bj < 2; ++bj) { const int col = u.pn * BM + bj * HALF + wc * 32 + 8 * fq;
;                     f32x4 v0, v1;
;                     if (xin_p) { const float* xr = (row < MP ? xin_p + (size_t)row * DM : xin_s + (size_t)(row - MP) * DM) + col; v0 = *(const f32x4*)xr; v1 = *(const f32x4*)(xr + 4); }
;                     else { const u32x4 w = *(const u32x4*)(XR + (size_t)row * DM + col);
;                         v0 = (f32x4){__uint_as_float(w.x << 16), __uint_as_float(w.x & 0xffff0000u), __uint_as_float(w.y << 16), __uint_as_float(w.y & 0xffff0000u)};
;                         v1 = (f32x4){__uint_as_float(w.z << 16), __uint_as_float(w.z & 0xffff0000u), __uint_as_float(w.w << 16), __uint_as_float(w.w & 0xffff0000u)}; }
;                     v0 = v0 + acc[ai][bj][m][0]; v1 = v1 + acc[ai][bj][m][1];
;                     if (fout) { *(f32x4*)(fout + (size_t)row * DM + col) = v0; *(f32x4*)(fout + (size_t)row * DM + col + 4) = v1; }
;                     else { u32x4 w; w.x = cvtpk(v0[0], v0[1]); w.y = cvtpk(v0[2], v0[3]); w.z = cvtpk(v1[0], v1[1]); w.w = cvtpk(v1[2], v1[3]); *(u32x4*)(XR + (size_t)row * DM + col) = w; }
.LBB0_952:
	v_add_u32_e32 v16, 0xb0, v140
	v_ashrrev_i32_e32 v17, 31, v16
	v_lshlrev_b64 v[18:19], 11, v[16:17]
	v_lshl_add_u64 v[18:19], s[12:13], 0, v[18:19]
	v_lshl_add_u64 v[18:19], v[138:139], 1, v[18:19]
	v_lshlrev_b64 v[24:25], 10, v[16:17]
	s_and_b64 vcc, exec, s[6:7]
	s_waitcnt vmcnt(15)
	v_mov_b32_e32 v20, v246
	v_mov_b32_e32 v21, v247
	v_mov_b32_e32 v22, v248
	v_mov_b32_e32 v23, v249
	v_lshlrev_b32_e32 v26, 16, v20
	v_and_b32_e32 v27, 0xffff0000, v20
	v_lshlrev_b32_e32 v20, 16, v21
	v_and_b32_e32 v21, 0xffff0000, v21
	v_lshlrev_b32_e32 v28, 16, v22
	v_and_b32_e32 v29, 0xffff0000, v22
	v_lshlrev_b32_e32 v22, 16, v23
	v_and_b32_e32 v23, 0xffff0000, v23
	v_pk_add_f32 v[14:15], v[14:15], v[20:21]
	v_pk_add_f32 v[12:13], v[12:13], v[26:27]
	v_pk_add_f32 v[10:11], v[10:11], v[22:23]
	v_pk_add_f32 v[8:9], v[8:9], v[28:29]
	v_lshl_add_u64 v[20:21], v[24:25], 2, s[16:17]
	s_cbranch_vccnz .LBB0_979
	v_lshl_add_u64 v[22:23], v[138:139], 2, v[20:21]
	global_store_dwordx4 v[22:23], v[12:15], off
	global_store_dwordx4 v[22:23], v[8:11], off offset:16
	s_cbranch_execnz .LBB0_955

; __device__ __forceinline__ unsigned cvtpk(float lo, float hi) { f32x2 v = {lo, hi}; bf16x2_t b = __builtin_convertvector(v, bf16x2_t); return __builtin_bit_cast(unsigned, b); }
;     __device__ __forceinline__ void operator()(const f32x4 (&acc)[2][2][4][2], const Unit& u, int wr, int wc, int fr, int fq) const {
;     ...
;                 for (int bj = 0; bj < 2; ++bj) { const int col = u.pn * BM + bj * HALF + wc * 32 + 8 * fq;
;                     f32x4 v0, v1;
;                     if (xin_p) { const float* xr = (row < MP ? xin_p + (size_t)row * DM : xin_s + (size_t)(row - MP) * DM) + col; v0 = *(const f32x4*)xr; v1 = *(const f32x4*)(xr + 4); }
;                     else { const u32x4 w = *(const u32x4*)(XR + (size_t)row * DM + col);
;                         v0 = (f32x4){__uint_as_float(w.x << 16), __uint_as_float(w.x & 0xffff0000u), __uint_as_float(w.y << 16), __uint_as_float(w.y & 0xffff0000u)};
;                         v1 = (f32x4){__uint_as_float(w.z << 16), __uint_as_float(w.z & 0xffff0000u), __uint_as_float(w.w << 16), __uint_as_float(w.w & 0xffff0000u)}; }
;                     v0 = v0 + acc[ai][bj][m][0]; v1 = v1 + acc[ai][bj][m][1];
;                     if (fout) { *(f32x4*)(fout + (size_t)row * DM + col) = v0; *(f32x4*)(fout + (size_t)row * DM + col + 4) = v1; }
;                     else { u32x4 w; w.x = cvtpk(v0[0], v0[1]); w.y = cvtpk(v0[2], v0[3]); w.z = cvtpk(v1[0], v1[1]); w.w = cvtpk(v1[2], v1[3]); *(u32x4*)(XR + (size_t)row * DM + col) = w; }
.LBB0_955:
	s_and_b64 vcc, exec, s[6:7]
	s_waitcnt vmcnt(15)
	v_mov_b32_e32 v22, v250
	v_mov_b32_e32 v23, v251
	v_mov_b32_e32 v24, v252
	v_mov_b32_e32 v25, v253
	v_lshlrev_b32_e32 v26, 16, v22
	v_and_b32_e32 v27, 0xffff0000, v22
	v_lshlrev_b32_e32 v22, 16, v23
	v_and_b32_e32 v23, 0xffff0000, v23
	v_lshlrev_b32_e32 v28, 16, v24
	v_and_b32_e32 v29, 0xffff0000, v24
	v_lshlrev_b32_e32 v24, 16, v25
	v_and_b32_e32 v25, 0xffff0000, v25
	v_pk_add_f32 v[6:7], v[6:7], v[22:23]
	v_pk_add_f32 v[4:5], v[4:5], v[26:27]
	v_pk_add_f32 v[2:3], v[2:3], v[24:25]
	v_pk_add_f32 v[0:1], v[0:1], v[28:29]
	s_cbranch_vccnz .LBB0_980
	v_lshl_add_u64 v[20:21], v[138:139], 2, v[20:21]
	global_store_dwordx4 v[20:21], v[4:7], off offset:512
	global_store_dwordx4 v[20:21], v[0:3], off offset:528
	s_cbranch_execnz .LBB0_958
